# GEMM unit loops: accumulator clear removed, first K-iteration peeled with C=0 MFMAs
# speedup vs baseline: 1.0214x; 1.0069x over previous
.LBB0_757:
	s_ashr_i32 s17, s16, 31
	s_lshl_b64 s[18:19], s[16:17], 20
	s_add_u32 s18, s35, s18
	s_addc_u32 s19, s40, s19
	s_and_b64 s[20:21], s[4:5], exec
	s_cselect_b32 s17, s19, s29
	s_cselect_b32 s23, s18, s28
	s_ashr_i32 s15, s14, 31
	s_lshl_b64 s[20:21], s[14:15], 19
	s_add_u32 s20, s38, s20
	s_addc_u32 s21, s39, s21
	s_and_b64 s[30:31], s[4:5], exec
	s_cselect_b32 s15, s21, s27
	s_cselect_b32 s25, s20, s26
	s_add_u32 s52, s26, 0x100
	s_addc_u32 s53, s27, 0
	s_add_u32 s26, s28, 0x80080
	s_addc_u32 s27, s29, 0
	s_mov_b32 s54, -2
	s_waitcnt lgkmcnt(0)
	s_add_u32 s28, s26, 0xfff80080
	s_addc_u32 s29, s27, -1
	s_add_i32 s55, 0, 0x10000
	s_cmp_eq_u32 s54, 12
	s_cselect_b32 s31, s17, s29
	s_cselect_b32 s30, s23, s28
	s_cselect_b32 s29, s15, s53
	s_cselect_b32 s28, s25, s52
	s_add_i32 s58, 0, 0x14000
	v_add_u32_e32 v156, s55, v145
	v_add_u32_e32 v172, s58, v145
	ds_read_b128 v[140:143], v156
	ds_read_b128 v[148:151], v156 offset:1024
	ds_read_b128 v[152:155], v156 offset:2048
	ds_read_b128 v[156:159], v156 offset:3072
	ds_read_b128 v[160:163], v172
	ds_read_b128 v[164:167], v172 offset:1024
	ds_read_b128 v[168:171], v172 offset:2048
	ds_read_b128 v[172:175], v172 offset:3072
	v_lshl_add_u64 v[188:189], s[26:27], 0, v[138:139]
	s_add_i32 m0, s42, 0xc000
	ds_read_b128 v[176:179], v147
	ds_read_b128 v[180:183], v147 offset:1024
	ds_read_b128 v[184:187], v147 offset:2048
	ds_read_b128 v[208:211], v147 offset:3072
	ds_read_b128 v[230:233], v147 offset:4096
	ds_read_b128 v[234:237], v147 offset:5120
	ds_read_b128 v[238:241], v147 offset:6144
	ds_read_b128 v[242:245], v147 offset:7168
	global_load_lds_dwordx4 v[188:189], off
	v_lshl_add_u64 v[188:189], s[26:27], 0, v[136:137]
	s_add_i32 m0, s42, 0xe000
	s_nop 0
	global_load_lds_dwordx4 v[188:189], off
	s_waitcnt vmcnt(8)
	s_waitcnt lgkmcnt(0)
	s_barrier
	s_setprio 1
	s_waitcnt lgkmcnt(0)
	v_mfma_f32_16x16x32_bf16 v[126:129], v[140:143], v[176:179], 0
	v_mfma_f32_16x16x32_bf16 v[122:125], v[152:155], v[176:179], 0
	v_mfma_f32_16x16x32_bf16 v[108:111], v[140:143], v[184:187], 0
	v_mfma_f32_16x16x32_bf16 v[104:107], v[152:155], v[184:187], 0
	v_mfma_f32_16x16x32_bf16 v[92:95], v[140:143], v[230:233], 0
	v_mfma_f32_16x16x32_bf16 v[88:91], v[152:155], v[230:233], 0
	v_mfma_f32_16x16x32_bf16 v[76:79], v[140:143], v[238:241], 0
	v_mfma_f32_16x16x32_bf16 v[72:75], v[152:155], v[238:241], 0
	v_mfma_f32_16x16x32_bf16 v[126:129], v[148:151], v[180:183], v[126:129]
	v_mfma_f32_16x16x32_bf16 v[122:125], v[156:159], v[180:183], v[122:125]
	v_mfma_f32_16x16x32_bf16 v[108:111], v[148:151], v[208:211], v[108:111]
	v_mfma_f32_16x16x32_bf16 v[104:107], v[156:159], v[208:211], v[104:107]
	v_mfma_f32_16x16x32_bf16 v[92:95], v[148:151], v[234:237], v[92:95]
	v_mfma_f32_16x16x32_bf16 v[88:91], v[156:159], v[234:237], v[88:91]
	v_mfma_f32_16x16x32_bf16 v[76:79], v[148:151], v[242:245], v[76:79]
	v_mfma_f32_16x16x32_bf16 v[72:75], v[156:159], v[242:245], v[72:75]
	s_setprio 0
	s_setprio 1
	v_mfma_f32_16x16x32_bf16 v[118:121], v[160:163], v[176:179], 0
	v_mfma_f32_16x16x32_bf16 v[114:117], v[168:171], v[176:179], 0
	v_mfma_f32_16x16x32_bf16 v[100:103], v[160:163], v[184:187], 0
	v_mfma_f32_16x16x32_bf16 v[96:99], v[168:171], v[184:187], 0
	v_mfma_f32_16x16x32_bf16 v[84:87], v[160:163], v[230:233], 0
	v_mfma_f32_16x16x32_bf16 v[80:83], v[168:171], v[230:233], 0
	v_mfma_f32_16x16x32_bf16 v[68:71], v[160:163], v[238:241], 0
	v_mfma_f32_16x16x32_bf16 v[64:67], v[168:171], v[238:241], 0
	v_mfma_f32_16x16x32_bf16 v[118:121], v[164:167], v[180:183], v[118:121]
	v_mfma_f32_16x16x32_bf16 v[114:117], v[172:175], v[180:183], v[114:117]
	v_mfma_f32_16x16x32_bf16 v[100:103], v[164:167], v[208:211], v[100:103]
	v_mfma_f32_16x16x32_bf16 v[96:99], v[172:175], v[208:211], v[96:99]
	v_mfma_f32_16x16x32_bf16 v[84:87], v[164:167], v[234:237], v[84:87]
	v_mfma_f32_16x16x32_bf16 v[80:83], v[172:175], v[234:237], v[80:83]
	v_mfma_f32_16x16x32_bf16 v[68:71], v[164:167], v[242:245], v[68:71]
	v_mfma_f32_16x16x32_bf16 v[64:67], v[172:175], v[242:245], v[64:67]
	s_setprio 0
	s_barrier
	s_add_i32 s55, s55, s41
	v_lshl_add_u64 v[188:189], s[28:29], 0, v[112:113]
	s_mov_b32 m0, s55
	ds_read_b128 v[176:179], v147 offset:16384
	ds_read_b128 v[180:183], v147 offset:17408
	ds_read_b128 v[184:187], v147 offset:18432
	ds_read_b128 v[208:211], v147 offset:19456
	ds_read_b128 v[230:233], v147 offset:20480
	ds_read_b128 v[234:237], v147 offset:21504
	ds_read_b128 v[238:241], v147 offset:22528
	ds_read_b128 v[242:245], v147 offset:23552
	global_load_lds_dwordx4 v[188:189], off
	s_add_i32 m0, s55, 0x2000
	s_add_u32 s56, s28, 0x40000
	v_lshl_add_u64 v[212:213], s[28:29], 0, v[134:135]
	s_addc_u32 s57, s29, 0
	s_add_i32 s55, s58, s41
	global_load_lds_dwordx4 v[212:213], off
	v_lshl_add_u64 v[228:229], s[56:57], 0, v[112:113]
	s_mov_b32 m0, s55
	v_lshl_add_u64 v[246:247], s[30:31], 0, v[132:133]
	global_load_lds_dwordx4 v[228:229], off
	v_lshl_add_u64 v[228:229], s[56:57], 0, v[134:135]
	s_add_i32 m0, s55, 0x2000
	s_nop 0
	global_load_lds_dwordx4 v[228:229], off
	v_lshl_add_u64 v[228:229], s[30:31], 0, v[130:131]
	s_mov_b32 m0, s42
	s_nop 0
	global_load_lds_dwordx4 v[228:229], off
	s_mov_b32 m0, s43
	s_nop 0
	global_load_lds_dwordx4 v[246:247], off
	s_waitcnt vmcnt(8)
	s_waitcnt lgkmcnt(0)
	s_barrier
	s_setprio 1
	s_waitcnt lgkmcnt(0)
	v_mfma_f32_16x16x32_bf16 v[60:63], v[140:143], v[176:179], 0
	v_mfma_f32_16x16x32_bf16 v[56:59], v[152:155], v[176:179], 0
	v_mfma_f32_16x16x32_bf16 v[44:47], v[140:143], v[184:187], 0
	v_mfma_f32_16x16x32_bf16 v[40:43], v[152:155], v[184:187], 0
	v_mfma_f32_16x16x32_bf16 v[28:31], v[140:143], v[230:233], 0
	v_mfma_f32_16x16x32_bf16 v[24:27], v[152:155], v[230:233], 0
	v_mfma_f32_16x16x32_bf16 v[12:15], v[140:143], v[238:241], 0
	v_mfma_f32_16x16x32_bf16 v[8:11], v[152:155], v[238:241], 0
	v_mfma_f32_16x16x32_bf16 v[60:63], v[148:151], v[180:183], v[60:63]
	v_mfma_f32_16x16x32_bf16 v[56:59], v[156:159], v[180:183], v[56:59]
	v_mfma_f32_16x16x32_bf16 v[44:47], v[148:151], v[208:211], v[44:47]
	v_mfma_f32_16x16x32_bf16 v[40:43], v[156:159], v[208:211], v[40:43]
	v_mfma_f32_16x16x32_bf16 v[28:31], v[148:151], v[234:237], v[28:31]
	v_mfma_f32_16x16x32_bf16 v[24:27], v[156:159], v[234:237], v[24:27]
	v_mfma_f32_16x16x32_bf16 v[12:15], v[148:151], v[242:245], v[12:15]
	v_mfma_f32_16x16x32_bf16 v[8:11], v[156:159], v[242:245], v[8:11]
	s_setprio 0
	s_setprio 1
	v_mfma_f32_16x16x32_bf16 v[52:55], v[160:163], v[176:179], 0
	v_mfma_f32_16x16x32_bf16 v[48:51], v[168:171], v[176:179], 0
	v_mfma_f32_16x16x32_bf16 v[36:39], v[160:163], v[184:187], 0
	v_mfma_f32_16x16x32_bf16 v[32:35], v[168:171], v[184:187], 0
	v_mfma_f32_16x16x32_bf16 v[20:23], v[160:163], v[230:233], 0
	v_mfma_f32_16x16x32_bf16 v[16:19], v[168:171], v[230:233], 0
	v_mfma_f32_16x16x32_bf16 v[4:7], v[160:163], v[238:241], 0
	v_mfma_f32_16x16x32_bf16 v[0:3], v[168:171], v[238:241], 0
	v_mfma_f32_16x16x32_bf16 v[52:55], v[164:167], v[180:183], v[52:55]
	v_mfma_f32_16x16x32_bf16 v[48:51], v[172:175], v[180:183], v[48:51]
	v_mfma_f32_16x16x32_bf16 v[36:39], v[164:167], v[208:211], v[36:39]
	v_mfma_f32_16x16x32_bf16 v[32:35], v[172:175], v[208:211], v[32:35]
	v_mfma_f32_16x16x32_bf16 v[20:23], v[164:167], v[234:237], v[20:23]
	v_mfma_f32_16x16x32_bf16 v[16:19], v[172:175], v[234:237], v[16:19]
	v_mfma_f32_16x16x32_bf16 v[4:7], v[164:167], v[242:245], v[4:7]
	v_mfma_f32_16x16x32_bf16 v[0:3], v[172:175], v[242:245], v[0:3]
	s_setprio 0
	s_barrier
	s_add_i32 s55, 0, 0x18000
	s_add_i32 s56, 0, 0x1c000
	v_add_u32_e32 v156, s55, v145
	v_add_u32_e32 v172, s56, v145
	ds_read_b128 v[140:143], v156
	ds_read_b128 v[148:151], v156 offset:1024
	ds_read_b128 v[152:155], v156 offset:2048
	ds_read_b128 v[156:159], v156 offset:3072
	ds_read_b128 v[160:163], v172
	ds_read_b128 v[164:167], v172 offset:1024
	ds_read_b128 v[168:171], v172 offset:2048
	ds_read_b128 v[172:175], v172 offset:3072
	s_add_u32 s30, s30, 0x80000
	s_addc_u32 s31, s31, 0
	s_mov_b32 m0, s44
	v_lshl_add_u64 v[248:249], s[30:31], 0, v[130:131]
	ds_read_b128 v[176:179], v147 offset:32768
	ds_read_b128 v[180:183], v147 offset:33792
	ds_read_b128 v[184:187], v147 offset:34816
	ds_read_b128 v[208:211], v147 offset:35840
	ds_read_b128 v[230:233], v147 offset:36864
	ds_read_b128 v[234:237], v147 offset:37888
	ds_read_b128 v[238:241], v147 offset:38912
	ds_read_b128 v[242:245], v147 offset:39936
	global_load_lds_dwordx4 v[248:249], off
	v_lshl_add_u64 v[248:249], s[30:31], 0, v[132:133]
	s_mov_b32 m0, s45
	s_nop 0
	global_load_lds_dwordx4 v[248:249], off
	s_waitcnt vmcnt(8)
	s_waitcnt lgkmcnt(0)
	s_barrier
	s_setprio 1
	s_waitcnt lgkmcnt(0)
	v_mfma_f32_16x16x32_bf16 v[126:129], v[140:143], v[176:179], v[126:129]
	v_mfma_f32_16x16x32_bf16 v[122:125], v[152:155], v[176:179], v[122:125]
	v_mfma_f32_16x16x32_bf16 v[108:111], v[140:143], v[184:187], v[108:111]
	v_mfma_f32_16x16x32_bf16 v[104:107], v[152:155], v[184:187], v[104:107]
	v_mfma_f32_16x16x32_bf16 v[92:95], v[140:143], v[230:233], v[92:95]
	v_mfma_f32_16x16x32_bf16 v[88:91], v[152:155], v[230:233], v[88:91]
	v_mfma_f32_16x16x32_bf16 v[76:79], v[140:143], v[238:241], v[76:79]
	v_mfma_f32_16x16x32_bf16 v[72:75], v[152:155], v[238:241], v[72:75]
	v_mfma_f32_16x16x32_bf16 v[126:129], v[148:151], v[180:183], v[126:129]
	v_mfma_f32_16x16x32_bf16 v[122:125], v[156:159], v[180:183], v[122:125]
	v_mfma_f32_16x16x32_bf16 v[108:111], v[148:151], v[208:211], v[108:111]
	v_mfma_f32_16x16x32_bf16 v[104:107], v[156:159], v[208:211], v[104:107]
	v_mfma_f32_16x16x32_bf16 v[92:95], v[148:151], v[234:237], v[92:95]
	v_mfma_f32_16x16x32_bf16 v[88:91], v[156:159], v[234:237], v[88:91]
	v_mfma_f32_16x16x32_bf16 v[76:79], v[148:151], v[242:245], v[76:79]
	v_mfma_f32_16x16x32_bf16 v[72:75], v[156:159], v[242:245], v[72:75]
	s_setprio 0
	s_setprio 1
	v_mfma_f32_16x16x32_bf16 v[118:121], v[160:163], v[176:179], v[118:121]
	v_mfma_f32_16x16x32_bf16 v[114:117], v[168:171], v[176:179], v[114:117]
	v_mfma_f32_16x16x32_bf16 v[100:103], v[160:163], v[184:187], v[100:103]
	v_mfma_f32_16x16x32_bf16 v[96:99], v[168:171], v[184:187], v[96:99]
	v_mfma_f32_16x16x32_bf16 v[84:87], v[160:163], v[230:233], v[84:87]
	v_mfma_f32_16x16x32_bf16 v[80:83], v[168:171], v[230:233], v[80:83]
	v_mfma_f32_16x16x32_bf16 v[68:71], v[160:163], v[238:241], v[68:71]
	v_mfma_f32_16x16x32_bf16 v[64:67], v[168:171], v[238:241], v[64:67]
	v_mfma_f32_16x16x32_bf16 v[118:121], v[164:167], v[180:183], v[118:121]
	v_mfma_f32_16x16x32_bf16 v[114:117], v[172:175], v[180:183], v[114:117]
	v_mfma_f32_16x16x32_bf16 v[100:103], v[164:167], v[208:211], v[100:103]
	v_mfma_f32_16x16x32_bf16 v[96:99], v[172:175], v[208:211], v[96:99]
	v_mfma_f32_16x16x32_bf16 v[84:87], v[164:167], v[234:237], v[84:87]
	v_mfma_f32_16x16x32_bf16 v[80:83], v[172:175], v[234:237], v[80:83]
	v_mfma_f32_16x16x32_bf16 v[68:71], v[164:167], v[242:245], v[68:71]
	v_mfma_f32_16x16x32_bf16 v[64:67], v[172:175], v[242:245], v[64:67]
	s_setprio 0
	s_barrier
	s_add_i32 s30, s55, s41
	v_lshl_add_u64 v[188:189], v[188:189], 0, s[96:97]
	s_mov_b32 m0, s30
	ds_read_b128 v[176:179], v147 offset:49152
	ds_read_b128 v[180:183], v147 offset:50176
	ds_read_b128 v[184:187], v147 offset:51200
	ds_read_b128 v[208:211], v147 offset:52224
	ds_read_b128 v[230:233], v147 offset:53248
	ds_read_b128 v[234:237], v147 offset:54272
	ds_read_b128 v[238:241], v147 offset:55296
	ds_read_b128 v[242:245], v147 offset:56320
	global_load_lds_dwordx4 v[188:189], off
	s_add_i32 m0, s30, 0x2000
	s_add_u32 s28, s28, 0x40080
	v_lshl_add_u64 v[188:189], v[212:213], 0, s[96:97]
	s_addc_u32 s29, s29, 0
	s_add_i32 s30, s56, s41
	global_load_lds_dwordx4 v[188:189], off
	v_lshl_add_u64 v[188:189], s[28:29], 0, v[112:113]
	s_mov_b32 m0, s30
	s_nop 0
	global_load_lds_dwordx4 v[188:189], off
	v_lshl_add_u64 v[188:189], s[28:29], 0, v[134:135]
	s_add_i32 m0, s30, 0x2000
	s_nop 0
	global_load_lds_dwordx4 v[188:189], off
	v_lshl_add_u64 v[188:189], v[228:229], 0, s[96:97]
	s_mov_b32 m0, s47
	s_nop 0
	global_load_lds_dwordx4 v[188:189], off
	v_lshl_add_u64 v[188:189], v[246:247], 0, s[96:97]
	s_mov_b32 m0, s48
	s_nop 0
	global_load_lds_dwordx4 v[188:189], off
	s_waitcnt vmcnt(8)
	s_waitcnt lgkmcnt(0)
	s_barrier
	s_setprio 1
	s_waitcnt lgkmcnt(0)
	v_mfma_f32_16x16x32_bf16 v[60:63], v[140:143], v[176:179], v[60:63]
	v_mfma_f32_16x16x32_bf16 v[56:59], v[152:155], v[176:179], v[56:59]
	v_mfma_f32_16x16x32_bf16 v[44:47], v[140:143], v[184:187], v[44:47]
	v_mfma_f32_16x16x32_bf16 v[40:43], v[152:155], v[184:187], v[40:43]
	v_mfma_f32_16x16x32_bf16 v[28:31], v[140:143], v[230:233], v[28:31]
	v_mfma_f32_16x16x32_bf16 v[24:27], v[152:155], v[230:233], v[24:27]
	v_mfma_f32_16x16x32_bf16 v[12:15], v[140:143], v[238:241], v[12:15]
	v_mfma_f32_16x16x32_bf16 v[8:11], v[152:155], v[238:241], v[8:11]
	v_mfma_f32_16x16x32_bf16 v[60:63], v[148:151], v[180:183], v[60:63]
	v_mfma_f32_16x16x32_bf16 v[56:59], v[156:159], v[180:183], v[56:59]
	v_mfma_f32_16x16x32_bf16 v[44:47], v[148:151], v[208:211], v[44:47]
	v_mfma_f32_16x16x32_bf16 v[40:43], v[156:159], v[208:211], v[40:43]
	v_mfma_f32_16x16x32_bf16 v[28:31], v[148:151], v[234:237], v[28:31]
	v_mfma_f32_16x16x32_bf16 v[24:27], v[156:159], v[234:237], v[24:27]
	v_mfma_f32_16x16x32_bf16 v[12:15], v[148:151], v[242:245], v[12:15]
	v_mfma_f32_16x16x32_bf16 v[8:11], v[156:159], v[242:245], v[8:11]
	s_setprio 0
	s_setprio 1
	v_mfma_f32_16x16x32_bf16 v[52:55], v[160:163], v[176:179], v[52:55]
	v_mfma_f32_16x16x32_bf16 v[48:51], v[168:171], v[176:179], v[48:51]
	v_mfma_f32_16x16x32_bf16 v[36:39], v[160:163], v[184:187], v[36:39]
	v_mfma_f32_16x16x32_bf16 v[32:35], v[168:171], v[184:187], v[32:35]
	v_mfma_f32_16x16x32_bf16 v[20:23], v[160:163], v[230:233], v[20:23]
	v_mfma_f32_16x16x32_bf16 v[16:19], v[168:171], v[230:233], v[16:19]
	v_mfma_f32_16x16x32_bf16 v[4:7], v[160:163], v[238:241], v[4:7]
	v_mfma_f32_16x16x32_bf16 v[0:3], v[168:171], v[238:241], v[0:3]
	v_mfma_f32_16x16x32_bf16 v[52:55], v[164:167], v[180:183], v[52:55]
	v_mfma_f32_16x16x32_bf16 v[48:51], v[172:175], v[180:183], v[48:51]
	v_mfma_f32_16x16x32_bf16 v[36:39], v[164:167], v[208:211], v[36:39]
	v_mfma_f32_16x16x32_bf16 v[32:35], v[172:175], v[208:211], v[32:35]
	v_mfma_f32_16x16x32_bf16 v[20:23], v[164:167], v[234:237], v[20:23]
	v_mfma_f32_16x16x32_bf16 v[16:19], v[172:175], v[234:237], v[16:19]
	v_mfma_f32_16x16x32_bf16 v[4:7], v[164:167], v[242:245], v[4:7]
	v_mfma_f32_16x16x32_bf16 v[0:3], v[172:175], v[242:245], v[0:3]
	s_setprio 0
	s_barrier
	s_add_i32 s54, s54, 2
	s_add_u32 s52, s52, 0x100
	s_addc_u32 s53, s53, 0
	s_add_u32 s26, s26, 0x100
	s_addc_u32 s27, s27, 0
	s_cmp_gt_u32 s54, 13
	s_cbranch_scc0 .LBB0_758
	s_branch .Lpeel_exit_758

.Lpeel_exit_758:
	s_and_b64 vcc, exec, s[12:13]
	s_cbranch_vccz .LBB0_761
	s_barrier

.LBB0_803:
	s_ashr_i32 s15, s14, 31
	s_lshl_b64 s[18:19], s[14:15], 20
	s_add_u32 s18, s38, s18
	s_addc_u32 s19, s39, s19
	s_and_b64 s[0:1], s[0:1], exec
	s_cselect_b32 s15, s19, s25
	s_cselect_b32 s21, s18, s24
	s_add_u32 s50, s24, 0x100
	s_addc_u32 s51, s25, 0
	s_mov_b32 s52, -2
	s_waitcnt lgkmcnt(0)
	s_add_u32 s0, s22, 0x100
	s_addc_u32 s1, s23, 0
	s_add_i32 s53, 0, 0x10000
	s_cmp_eq_u32 s52, 28
	s_cselect_b32 s27, s17, s1
	s_cselect_b32 s26, s16, s0
	s_cselect_b32 s25, s15, s51
	s_cselect_b32 s24, s21, s50
	s_add_i32 s54, 0, 0x14000
	v_add_u32_e32 v156, s53, v145
	v_add_u32_e32 v172, s54, v145
	ds_read_b128 v[140:143], v156
	ds_read_b128 v[148:151], v156 offset:1024
	ds_read_b128 v[152:155], v156 offset:2048
	ds_read_b128 v[156:159], v156 offset:3072
	ds_read_b128 v[160:163], v172
	ds_read_b128 v[164:167], v172 offset:1024
	ds_read_b128 v[168:171], v172 offset:2048
	ds_read_b128 v[172:175], v172 offset:3072
	v_lshl_add_u64 v[188:189], s[22:23], 0, v[138:139]
	s_add_i32 m0, s31, 0xc000
	ds_read_b128 v[176:179], v147
	ds_read_b128 v[180:183], v147 offset:1024
	ds_read_b128 v[184:187], v147 offset:2048
	ds_read_b128 v[208:211], v147 offset:3072
	ds_read_b128 v[230:233], v147 offset:4096
	ds_read_b128 v[234:237], v147 offset:5120
	ds_read_b128 v[238:241], v147 offset:6144
	ds_read_b128 v[242:245], v147 offset:7168
	global_load_lds_dwordx4 v[188:189], off
	v_lshl_add_u64 v[188:189], s[22:23], 0, v[136:137]
	s_add_i32 m0, s31, 0xe000
	s_nop 0
	global_load_lds_dwordx4 v[188:189], off
	s_waitcnt vmcnt(8)
	s_waitcnt lgkmcnt(0)
	s_barrier
	s_setprio 1
	s_waitcnt lgkmcnt(0)
	v_mfma_f32_16x16x32_bf16 v[126:129], v[140:143], v[176:179], 0
	v_mfma_f32_16x16x32_bf16 v[122:125], v[152:155], v[176:179], 0
	v_mfma_f32_16x16x32_bf16 v[108:111], v[140:143], v[184:187], 0
	v_mfma_f32_16x16x32_bf16 v[104:107], v[152:155], v[184:187], 0
	v_mfma_f32_16x16x32_bf16 v[92:95], v[140:143], v[230:233], 0
	v_mfma_f32_16x16x32_bf16 v[88:91], v[152:155], v[230:233], 0
	v_mfma_f32_16x16x32_bf16 v[76:79], v[140:143], v[238:241], 0
	v_mfma_f32_16x16x32_bf16 v[72:75], v[152:155], v[238:241], 0
	v_mfma_f32_16x16x32_bf16 v[126:129], v[148:151], v[180:183], v[126:129]
	v_mfma_f32_16x16x32_bf16 v[122:125], v[156:159], v[180:183], v[122:125]
	v_mfma_f32_16x16x32_bf16 v[108:111], v[148:151], v[208:211], v[108:111]
	v_mfma_f32_16x16x32_bf16 v[104:107], v[156:159], v[208:211], v[104:107]
	v_mfma_f32_16x16x32_bf16 v[92:95], v[148:151], v[234:237], v[92:95]
	v_mfma_f32_16x16x32_bf16 v[88:91], v[156:159], v[234:237], v[88:91]
	v_mfma_f32_16x16x32_bf16 v[76:79], v[148:151], v[242:245], v[76:79]
	v_mfma_f32_16x16x32_bf16 v[72:75], v[156:159], v[242:245], v[72:75]
	s_setprio 0
	s_setprio 1
	v_mfma_f32_16x16x32_bf16 v[118:121], v[160:163], v[176:179], 0
	v_mfma_f32_16x16x32_bf16 v[114:117], v[168:171], v[176:179], 0
	v_mfma_f32_16x16x32_bf16 v[100:103], v[160:163], v[184:187], 0
	v_mfma_f32_16x16x32_bf16 v[96:99], v[168:171], v[184:187], 0
	v_mfma_f32_16x16x32_bf16 v[84:87], v[160:163], v[230:233], 0
	v_mfma_f32_16x16x32_bf16 v[80:83], v[168:171], v[230:233], 0
	v_mfma_f32_16x16x32_bf16 v[68:71], v[160:163], v[238:241], 0
	v_mfma_f32_16x16x32_bf16 v[64:67], v[168:171], v[238:241], 0
	v_mfma_f32_16x16x32_bf16 v[118:121], v[164:167], v[180:183], v[118:121]
	v_mfma_f32_16x16x32_bf16 v[114:117], v[172:175], v[180:183], v[114:117]
	v_mfma_f32_16x16x32_bf16 v[100:103], v[164:167], v[208:211], v[100:103]
	v_mfma_f32_16x16x32_bf16 v[96:99], v[172:175], v[208:211], v[96:99]
	v_mfma_f32_16x16x32_bf16 v[84:87], v[164:167], v[234:237], v[84:87]
	v_mfma_f32_16x16x32_bf16 v[80:83], v[172:175], v[234:237], v[80:83]
	v_mfma_f32_16x16x32_bf16 v[68:71], v[164:167], v[242:245], v[68:71]
	v_mfma_f32_16x16x32_bf16 v[64:67], v[172:175], v[242:245], v[64:67]
	s_setprio 0
	s_barrier
	s_add_i32 s22, s53, s30
	v_lshl_add_u64 v[188:189], s[24:25], 0, v[112:113]
	s_mov_b32 m0, s22
	ds_read_b128 v[176:179], v147 offset:16384
	ds_read_b128 v[180:183], v147 offset:17408
	ds_read_b128 v[184:187], v147 offset:18432
	ds_read_b128 v[208:211], v147 offset:19456
	ds_read_b128 v[230:233], v147 offset:20480
	ds_read_b128 v[234:237], v147 offset:21504
	ds_read_b128 v[238:241], v147 offset:22528
	ds_read_b128 v[242:245], v147 offset:23552
	global_load_lds_dwordx4 v[188:189], off
	s_add_i32 m0, s22, 0x2000
	s_add_u32 s22, s24, 0x80000
	v_lshl_add_u64 v[212:213], s[24:25], 0, v[134:135]
	s_addc_u32 s23, s25, 0
	s_add_i32 s53, s54, s30
	global_load_lds_dwordx4 v[212:213], off
	v_lshl_add_u64 v[228:229], s[22:23], 0, v[112:113]
	s_mov_b32 m0, s53
	v_lshl_add_u64 v[246:247], s[26:27], 0, v[132:133]
	global_load_lds_dwordx4 v[228:229], off
	v_lshl_add_u64 v[228:229], s[22:23], 0, v[134:135]
	s_add_i32 m0, s53, 0x2000
	s_nop 0
	global_load_lds_dwordx4 v[228:229], off
	v_lshl_add_u64 v[228:229], s[26:27], 0, v[130:131]
	s_mov_b32 m0, s31
	s_nop 0
	global_load_lds_dwordx4 v[228:229], off
	s_mov_b32 m0, s35
	s_nop 0
	global_load_lds_dwordx4 v[246:247], off
	s_waitcnt vmcnt(8)
	s_waitcnt lgkmcnt(0)
	s_barrier
	s_setprio 1
	s_waitcnt lgkmcnt(0)
	v_mfma_f32_16x16x32_bf16 v[60:63], v[140:143], v[176:179], 0
	v_mfma_f32_16x16x32_bf16 v[56:59], v[152:155], v[176:179], 0
	v_mfma_f32_16x16x32_bf16 v[44:47], v[140:143], v[184:187], 0
	v_mfma_f32_16x16x32_bf16 v[40:43], v[152:155], v[184:187], 0
	v_mfma_f32_16x16x32_bf16 v[28:31], v[140:143], v[230:233], 0
	v_mfma_f32_16x16x32_bf16 v[24:27], v[152:155], v[230:233], 0
	v_mfma_f32_16x16x32_bf16 v[12:15], v[140:143], v[238:241], 0
	v_mfma_f32_16x16x32_bf16 v[8:11], v[152:155], v[238:241], 0
	v_mfma_f32_16x16x32_bf16 v[60:63], v[148:151], v[180:183], v[60:63]
	v_mfma_f32_16x16x32_bf16 v[56:59], v[156:159], v[180:183], v[56:59]
	v_mfma_f32_16x16x32_bf16 v[44:47], v[148:151], v[208:211], v[44:47]
	v_mfma_f32_16x16x32_bf16 v[40:43], v[156:159], v[208:211], v[40:43]
	v_mfma_f32_16x16x32_bf16 v[28:31], v[148:151], v[234:237], v[28:31]
	v_mfma_f32_16x16x32_bf16 v[24:27], v[156:159], v[234:237], v[24:27]
	v_mfma_f32_16x16x32_bf16 v[12:15], v[148:151], v[242:245], v[12:15]
	v_mfma_f32_16x16x32_bf16 v[8:11], v[156:159], v[242:245], v[8:11]
	s_setprio 0
	s_setprio 1
	v_mfma_f32_16x16x32_bf16 v[52:55], v[160:163], v[176:179], 0
	v_mfma_f32_16x16x32_bf16 v[48:51], v[168:171], v[176:179], 0
	v_mfma_f32_16x16x32_bf16 v[36:39], v[160:163], v[184:187], 0
	v_mfma_f32_16x16x32_bf16 v[32:35], v[168:171], v[184:187], 0
	v_mfma_f32_16x16x32_bf16 v[20:23], v[160:163], v[230:233], 0
	v_mfma_f32_16x16x32_bf16 v[16:19], v[168:171], v[230:233], 0
	v_mfma_f32_16x16x32_bf16 v[4:7], v[160:163], v[238:241], 0
	v_mfma_f32_16x16x32_bf16 v[0:3], v[168:171], v[238:241], 0
	v_mfma_f32_16x16x32_bf16 v[52:55], v[164:167], v[180:183], v[52:55]
	v_mfma_f32_16x16x32_bf16 v[48:51], v[172:175], v[180:183], v[48:51]
	v_mfma_f32_16x16x32_bf16 v[36:39], v[164:167], v[208:211], v[36:39]
	v_mfma_f32_16x16x32_bf16 v[32:35], v[172:175], v[208:211], v[32:35]
	v_mfma_f32_16x16x32_bf16 v[20:23], v[164:167], v[234:237], v[20:23]
	v_mfma_f32_16x16x32_bf16 v[16:19], v[172:175], v[234:237], v[16:19]
	v_mfma_f32_16x16x32_bf16 v[4:7], v[164:167], v[242:245], v[4:7]
	v_mfma_f32_16x16x32_bf16 v[0:3], v[172:175], v[242:245], v[0:3]
	s_setprio 0
	s_barrier
	s_add_i32 s53, 0, 0x18000
	s_add_i32 s54, 0, 0x1c000
	v_add_u32_e32 v156, s53, v145
	v_add_u32_e32 v172, s54, v145
	ds_read_b128 v[140:143], v156
	ds_read_b128 v[148:151], v156 offset:1024
	ds_read_b128 v[152:155], v156 offset:2048
	ds_read_b128 v[156:159], v156 offset:3072
	ds_read_b128 v[160:163], v172
	ds_read_b128 v[164:167], v172 offset:1024
	ds_read_b128 v[168:171], v172 offset:2048
	ds_read_b128 v[172:175], v172 offset:3072
	s_add_u32 s22, s26, 0x120000
	s_addc_u32 s23, s27, 0
	s_mov_b32 m0, s40
	v_lshl_add_u64 v[248:249], s[22:23], 0, v[130:131]
	ds_read_b128 v[176:179], v147 offset:32768
	ds_read_b128 v[180:183], v147 offset:33792
	ds_read_b128 v[184:187], v147 offset:34816
	ds_read_b128 v[208:211], v147 offset:35840
	ds_read_b128 v[230:233], v147 offset:36864
	ds_read_b128 v[234:237], v147 offset:37888
	ds_read_b128 v[238:241], v147 offset:38912
	ds_read_b128 v[242:245], v147 offset:39936
	global_load_lds_dwordx4 v[248:249], off
	v_lshl_add_u64 v[248:249], s[22:23], 0, v[132:133]
	s_mov_b32 m0, s41
	s_nop 0
	global_load_lds_dwordx4 v[248:249], off
	s_waitcnt vmcnt(8)
	s_waitcnt lgkmcnt(0)
	s_barrier
	s_setprio 1
	s_waitcnt lgkmcnt(0)
	v_mfma_f32_16x16x32_bf16 v[126:129], v[140:143], v[176:179], v[126:129]
	v_mfma_f32_16x16x32_bf16 v[122:125], v[152:155], v[176:179], v[122:125]
	v_mfma_f32_16x16x32_bf16 v[108:111], v[140:143], v[184:187], v[108:111]
	v_mfma_f32_16x16x32_bf16 v[104:107], v[152:155], v[184:187], v[104:107]
	v_mfma_f32_16x16x32_bf16 v[92:95], v[140:143], v[230:233], v[92:95]
	v_mfma_f32_16x16x32_bf16 v[88:91], v[152:155], v[230:233], v[88:91]
	v_mfma_f32_16x16x32_bf16 v[76:79], v[140:143], v[238:241], v[76:79]
	v_mfma_f32_16x16x32_bf16 v[72:75], v[152:155], v[238:241], v[72:75]
	v_mfma_f32_16x16x32_bf16 v[126:129], v[148:151], v[180:183], v[126:129]
	v_mfma_f32_16x16x32_bf16 v[122:125], v[156:159], v[180:183], v[122:125]
	v_mfma_f32_16x16x32_bf16 v[108:111], v[148:151], v[208:211], v[108:111]
	v_mfma_f32_16x16x32_bf16 v[104:107], v[156:159], v[208:211], v[104:107]
	v_mfma_f32_16x16x32_bf16 v[92:95], v[148:151], v[234:237], v[92:95]
	v_mfma_f32_16x16x32_bf16 v[88:91], v[156:159], v[234:237], v[88:91]
	v_mfma_f32_16x16x32_bf16 v[76:79], v[148:151], v[242:245], v[76:79]
	v_mfma_f32_16x16x32_bf16 v[72:75], v[156:159], v[242:245], v[72:75]
	s_setprio 0
	s_setprio 1
	v_mfma_f32_16x16x32_bf16 v[118:121], v[160:163], v[176:179], v[118:121]
	v_mfma_f32_16x16x32_bf16 v[114:117], v[168:171], v[176:179], v[114:117]
	v_mfma_f32_16x16x32_bf16 v[100:103], v[160:163], v[184:187], v[100:103]
	v_mfma_f32_16x16x32_bf16 v[96:99], v[168:171], v[184:187], v[96:99]
	v_mfma_f32_16x16x32_bf16 v[84:87], v[160:163], v[230:233], v[84:87]
	v_mfma_f32_16x16x32_bf16 v[80:83], v[168:171], v[230:233], v[80:83]
	v_mfma_f32_16x16x32_bf16 v[68:71], v[160:163], v[238:241], v[68:71]
	v_mfma_f32_16x16x32_bf16 v[64:67], v[168:171], v[238:241], v[64:67]
	v_mfma_f32_16x16x32_bf16 v[118:121], v[164:167], v[180:183], v[118:121]
	v_mfma_f32_16x16x32_bf16 v[114:117], v[172:175], v[180:183], v[114:117]
	v_mfma_f32_16x16x32_bf16 v[100:103], v[164:167], v[208:211], v[100:103]
	v_mfma_f32_16x16x32_bf16 v[96:99], v[172:175], v[208:211], v[96:99]
	v_mfma_f32_16x16x32_bf16 v[84:87], v[164:167], v[234:237], v[84:87]
	v_mfma_f32_16x16x32_bf16 v[80:83], v[172:175], v[234:237], v[80:83]
	v_mfma_f32_16x16x32_bf16 v[68:71], v[164:167], v[242:245], v[68:71]
	v_mfma_f32_16x16x32_bf16 v[64:67], v[172:175], v[242:245], v[64:67]
	s_setprio 0
	s_barrier
	s_add_i32 s22, s53, s30
	v_lshl_add_u64 v[188:189], v[188:189], 0, s[96:97]
	s_mov_b32 m0, s22
	ds_read_b128 v[176:179], v147 offset:49152
	ds_read_b128 v[180:183], v147 offset:50176
	ds_read_b128 v[184:187], v147 offset:51200
	ds_read_b128 v[208:211], v147 offset:52224
	ds_read_b128 v[230:233], v147 offset:53248
	ds_read_b128 v[234:237], v147 offset:54272
	ds_read_b128 v[238:241], v147 offset:55296
	ds_read_b128 v[242:245], v147 offset:56320
	global_load_lds_dwordx4 v[188:189], off
	s_add_i32 m0, s22, 0x2000
	s_add_u32 s22, s24, 0x80080
	v_lshl_add_u64 v[188:189], v[212:213], 0, s[96:97]
	s_addc_u32 s23, s25, 0
	s_add_i32 s24, s54, s30
	global_load_lds_dwordx4 v[188:189], off
	v_lshl_add_u64 v[188:189], s[22:23], 0, v[112:113]
	s_mov_b32 m0, s24
	s_nop 0
	global_load_lds_dwordx4 v[188:189], off
	v_lshl_add_u64 v[188:189], s[22:23], 0, v[134:135]
	s_add_i32 m0, s24, 0x2000
	s_nop 0
	global_load_lds_dwordx4 v[188:189], off
	v_lshl_add_u64 v[188:189], v[228:229], 0, s[96:97]
	s_mov_b32 m0, s43
	s_nop 0
	global_load_lds_dwordx4 v[188:189], off
	v_lshl_add_u64 v[188:189], v[246:247], 0, s[96:97]
	s_mov_b32 m0, s44
	s_nop 0
	global_load_lds_dwordx4 v[188:189], off
	s_waitcnt vmcnt(8)
	s_waitcnt lgkmcnt(0)
	s_barrier
	s_setprio 1
	s_waitcnt lgkmcnt(0)
	v_mfma_f32_16x16x32_bf16 v[60:63], v[140:143], v[176:179], v[60:63]
	v_mfma_f32_16x16x32_bf16 v[56:59], v[152:155], v[176:179], v[56:59]
	v_mfma_f32_16x16x32_bf16 v[44:47], v[140:143], v[184:187], v[44:47]
	v_mfma_f32_16x16x32_bf16 v[40:43], v[152:155], v[184:187], v[40:43]
	v_mfma_f32_16x16x32_bf16 v[28:31], v[140:143], v[230:233], v[28:31]
	v_mfma_f32_16x16x32_bf16 v[24:27], v[152:155], v[230:233], v[24:27]
	v_mfma_f32_16x16x32_bf16 v[12:15], v[140:143], v[238:241], v[12:15]
	v_mfma_f32_16x16x32_bf16 v[8:11], v[152:155], v[238:241], v[8:11]
	v_mfma_f32_16x16x32_bf16 v[60:63], v[148:151], v[180:183], v[60:63]
	v_mfma_f32_16x16x32_bf16 v[56:59], v[156:159], v[180:183], v[56:59]
	v_mfma_f32_16x16x32_bf16 v[44:47], v[148:151], v[208:211], v[44:47]
	v_mfma_f32_16x16x32_bf16 v[40:43], v[156:159], v[208:211], v[40:43]
	v_mfma_f32_16x16x32_bf16 v[28:31], v[148:151], v[234:237], v[28:31]
	v_mfma_f32_16x16x32_bf16 v[24:27], v[156:159], v[234:237], v[24:27]
	v_mfma_f32_16x16x32_bf16 v[12:15], v[148:151], v[242:245], v[12:15]
	v_mfma_f32_16x16x32_bf16 v[8:11], v[156:159], v[242:245], v[8:11]
	s_setprio 0
	s_setprio 1
	v_mfma_f32_16x16x32_bf16 v[52:55], v[160:163], v[176:179], v[52:55]
	v_mfma_f32_16x16x32_bf16 v[48:51], v[168:171], v[176:179], v[48:51]
	v_mfma_f32_16x16x32_bf16 v[36:39], v[160:163], v[184:187], v[36:39]
	v_mfma_f32_16x16x32_bf16 v[32:35], v[168:171], v[184:187], v[32:35]
	v_mfma_f32_16x16x32_bf16 v[20:23], v[160:163], v[230:233], v[20:23]
	v_mfma_f32_16x16x32_bf16 v[16:19], v[168:171], v[230:233], v[16:19]
	v_mfma_f32_16x16x32_bf16 v[4:7], v[160:163], v[238:241], v[4:7]
	v_mfma_f32_16x16x32_bf16 v[0:3], v[168:171], v[238:241], v[0:3]
	v_mfma_f32_16x16x32_bf16 v[52:55], v[164:167], v[180:183], v[52:55]
	v_mfma_f32_16x16x32_bf16 v[48:51], v[172:175], v[180:183], v[48:51]
	v_mfma_f32_16x16x32_bf16 v[36:39], v[164:167], v[208:211], v[36:39]
	v_mfma_f32_16x16x32_bf16 v[32:35], v[172:175], v[208:211], v[32:35]
	v_mfma_f32_16x16x32_bf16 v[20:23], v[164:167], v[234:237], v[20:23]
	v_mfma_f32_16x16x32_bf16 v[16:19], v[172:175], v[234:237], v[16:19]
	v_mfma_f32_16x16x32_bf16 v[4:7], v[164:167], v[242:245], v[4:7]
	v_mfma_f32_16x16x32_bf16 v[0:3], v[172:175], v[242:245], v[0:3]
	s_setprio 0
	s_barrier
	s_add_i32 s52, s52, 2
	s_add_u32 s50, s50, 0x100
	s_addc_u32 s51, s51, 0
	s_cmp_gt_u32 s52, 29
	s_mov_b64 s[22:23], s[0:1]
	s_cbranch_scc0 .LBB0_804
	s_branch .Lpeel_exit_804

.LBB0_1136:
	s_add_u32 s48, s18, 0x100
	s_addc_u32 s49, s19, 0
	s_mov_b32 s50, -2
	s_waitcnt lgkmcnt(0)
	s_add_u32 s18, s16, 0x100
	s_addc_u32 s19, s17, 0
	s_add_i32 s51, 0, 0x10000
	s_cmp_eq_u32 s50, 40
	s_cselect_b32 s23, s1, s19
	s_cselect_b32 s22, s0, s18
	s_cselect_b32 s21, s15, s49
	s_cselect_b32 s20, s14, s48
	s_add_i32 s52, 0, 0x14000
	v_add_u32_e32 v156, s51, v145
	v_add_u32_e32 v172, s52, v145
	ds_read_b128 v[140:143], v156
	ds_read_b128 v[148:151], v156 offset:1024
	ds_read_b128 v[152:155], v156 offset:2048
	ds_read_b128 v[156:159], v156 offset:3072
	ds_read_b128 v[160:163], v172
	ds_read_b128 v[164:167], v172 offset:1024
	ds_read_b128 v[168:171], v172 offset:2048
	ds_read_b128 v[172:175], v172 offset:3072
	v_lshl_add_u64 v[188:189], s[16:17], 0, v[138:139]
	s_add_i32 m0, s31, 0xc000
	ds_read_b128 v[176:179], v147
	ds_read_b128 v[180:183], v147 offset:1024
	ds_read_b128 v[184:187], v147 offset:2048
	ds_read_b128 v[208:211], v147 offset:3072
	ds_read_b128 v[230:233], v147 offset:4096
	ds_read_b128 v[234:237], v147 offset:5120
	ds_read_b128 v[238:241], v147 offset:6144
	ds_read_b128 v[242:245], v147 offset:7168
	global_load_lds_dwordx4 v[188:189], off
	v_lshl_add_u64 v[188:189], s[16:17], 0, v[136:137]
	s_add_i32 m0, s31, 0xe000
	s_nop 0
	global_load_lds_dwordx4 v[188:189], off
	s_waitcnt vmcnt(8)
	s_waitcnt lgkmcnt(0)
	s_barrier
	s_setprio 1
	s_waitcnt lgkmcnt(0)
	v_mfma_f32_16x16x32_bf16 v[126:129], v[140:143], v[176:179], 0
	v_mfma_f32_16x16x32_bf16 v[122:125], v[152:155], v[176:179], 0
	v_mfma_f32_16x16x32_bf16 v[108:111], v[140:143], v[184:187], 0
	v_mfma_f32_16x16x32_bf16 v[104:107], v[152:155], v[184:187], 0
	v_mfma_f32_16x16x32_bf16 v[92:95], v[140:143], v[230:233], 0
	v_mfma_f32_16x16x32_bf16 v[88:91], v[152:155], v[230:233], 0
	v_mfma_f32_16x16x32_bf16 v[76:79], v[140:143], v[238:241], 0
	v_mfma_f32_16x16x32_bf16 v[72:75], v[152:155], v[238:241], 0
	v_mfma_f32_16x16x32_bf16 v[126:129], v[148:151], v[180:183], v[126:129]
	v_mfma_f32_16x16x32_bf16 v[122:125], v[156:159], v[180:183], v[122:125]
	v_mfma_f32_16x16x32_bf16 v[108:111], v[148:151], v[208:211], v[108:111]
	v_mfma_f32_16x16x32_bf16 v[104:107], v[156:159], v[208:211], v[104:107]
	v_mfma_f32_16x16x32_bf16 v[92:95], v[148:151], v[234:237], v[92:95]
	v_mfma_f32_16x16x32_bf16 v[88:91], v[156:159], v[234:237], v[88:91]
	v_mfma_f32_16x16x32_bf16 v[76:79], v[148:151], v[242:245], v[76:79]
	v_mfma_f32_16x16x32_bf16 v[72:75], v[156:159], v[242:245], v[72:75]
	s_setprio 0
	s_setprio 1
	v_mfma_f32_16x16x32_bf16 v[118:121], v[160:163], v[176:179], 0
	v_mfma_f32_16x16x32_bf16 v[114:117], v[168:171], v[176:179], 0
	v_mfma_f32_16x16x32_bf16 v[100:103], v[160:163], v[184:187], 0
	v_mfma_f32_16x16x32_bf16 v[96:99], v[168:171], v[184:187], 0
	v_mfma_f32_16x16x32_bf16 v[84:87], v[160:163], v[230:233], 0
	v_mfma_f32_16x16x32_bf16 v[80:83], v[168:171], v[230:233], 0
	v_mfma_f32_16x16x32_bf16 v[68:71], v[160:163], v[238:241], 0
	v_mfma_f32_16x16x32_bf16 v[64:67], v[168:171], v[238:241], 0
	v_mfma_f32_16x16x32_bf16 v[118:121], v[164:167], v[180:183], v[118:121]
	v_mfma_f32_16x16x32_bf16 v[114:117], v[172:175], v[180:183], v[114:117]
	v_mfma_f32_16x16x32_bf16 v[100:103], v[164:167], v[208:211], v[100:103]
	v_mfma_f32_16x16x32_bf16 v[96:99], v[172:175], v[208:211], v[96:99]
	v_mfma_f32_16x16x32_bf16 v[84:87], v[164:167], v[234:237], v[84:87]
	v_mfma_f32_16x16x32_bf16 v[80:83], v[172:175], v[234:237], v[80:83]
	v_mfma_f32_16x16x32_bf16 v[68:71], v[164:167], v[242:245], v[68:71]
	v_mfma_f32_16x16x32_bf16 v[64:67], v[172:175], v[242:245], v[64:67]
	s_setprio 0
	s_barrier
	s_add_i32 s16, s51, s30
	v_lshl_add_u64 v[188:189], s[20:21], 0, v[112:113]
	s_mov_b32 m0, s16
	ds_read_b128 v[176:179], v147 offset:16384
	ds_read_b128 v[180:183], v147 offset:17408
	ds_read_b128 v[184:187], v147 offset:18432
	ds_read_b128 v[208:211], v147 offset:19456
	ds_read_b128 v[230:233], v147 offset:20480
	ds_read_b128 v[234:237], v147 offset:21504
	ds_read_b128 v[238:241], v147 offset:22528
	ds_read_b128 v[242:245], v147 offset:23552
	global_load_lds_dwordx4 v[188:189], off
	s_add_i32 m0, s16, 0x2000
	s_add_u32 s16, s20, 0xb0000
	v_lshl_add_u64 v[212:213], s[20:21], 0, v[134:135]
	s_addc_u32 s17, s21, 0
	s_add_i32 s51, s52, s30
	global_load_lds_dwordx4 v[212:213], off
	v_lshl_add_u64 v[246:247], s[16:17], 0, v[112:113]
	s_mov_b32 m0, s51
	v_lshl_add_u64 v[248:249], s[22:23], 0, v[132:133]
	global_load_lds_dwordx4 v[246:247], off
	v_lshl_add_u64 v[246:247], s[16:17], 0, v[134:135]
	s_add_i32 m0, s51, 0x2000
	s_nop 0
	global_load_lds_dwordx4 v[246:247], off
	v_lshl_add_u64 v[246:247], s[22:23], 0, v[130:131]
	s_mov_b32 m0, s31
	s_nop 0
	global_load_lds_dwordx4 v[246:247], off
	s_mov_b32 m0, s35
	s_nop 0
	global_load_lds_dwordx4 v[248:249], off
	s_waitcnt vmcnt(8)
	s_waitcnt lgkmcnt(0)
	s_barrier
	s_setprio 1
	s_waitcnt lgkmcnt(0)
	v_mfma_f32_16x16x32_bf16 v[60:63], v[140:143], v[176:179], 0
	v_mfma_f32_16x16x32_bf16 v[56:59], v[152:155], v[176:179], 0
	v_mfma_f32_16x16x32_bf16 v[44:47], v[140:143], v[184:187], 0
	v_mfma_f32_16x16x32_bf16 v[40:43], v[152:155], v[184:187], 0
	v_mfma_f32_16x16x32_bf16 v[28:31], v[140:143], v[230:233], 0
	v_mfma_f32_16x16x32_bf16 v[24:27], v[152:155], v[230:233], 0
	v_mfma_f32_16x16x32_bf16 v[12:15], v[140:143], v[238:241], 0
	v_mfma_f32_16x16x32_bf16 v[8:11], v[152:155], v[238:241], 0
	v_mfma_f32_16x16x32_bf16 v[60:63], v[148:151], v[180:183], v[60:63]
	v_mfma_f32_16x16x32_bf16 v[56:59], v[156:159], v[180:183], v[56:59]
	v_mfma_f32_16x16x32_bf16 v[44:47], v[148:151], v[208:211], v[44:47]
	v_mfma_f32_16x16x32_bf16 v[40:43], v[156:159], v[208:211], v[40:43]
	v_mfma_f32_16x16x32_bf16 v[28:31], v[148:151], v[234:237], v[28:31]
	v_mfma_f32_16x16x32_bf16 v[24:27], v[156:159], v[234:237], v[24:27]
	v_mfma_f32_16x16x32_bf16 v[12:15], v[148:151], v[242:245], v[12:15]
	v_mfma_f32_16x16x32_bf16 v[8:11], v[156:159], v[242:245], v[8:11]
	s_setprio 0
	s_setprio 1
	v_mfma_f32_16x16x32_bf16 v[52:55], v[160:163], v[176:179], 0
	v_mfma_f32_16x16x32_bf16 v[48:51], v[168:171], v[176:179], 0
	v_mfma_f32_16x16x32_bf16 v[36:39], v[160:163], v[184:187], 0
	v_mfma_f32_16x16x32_bf16 v[32:35], v[168:171], v[184:187], 0
	v_mfma_f32_16x16x32_bf16 v[20:23], v[160:163], v[230:233], 0
	v_mfma_f32_16x16x32_bf16 v[16:19], v[168:171], v[230:233], 0
	v_mfma_f32_16x16x32_bf16 v[4:7], v[160:163], v[238:241], 0
	v_mfma_f32_16x16x32_bf16 v[0:3], v[168:171], v[238:241], 0
	v_mfma_f32_16x16x32_bf16 v[52:55], v[164:167], v[180:183], v[52:55]
	v_mfma_f32_16x16x32_bf16 v[48:51], v[172:175], v[180:183], v[48:51]
	v_mfma_f32_16x16x32_bf16 v[36:39], v[164:167], v[208:211], v[36:39]
	v_mfma_f32_16x16x32_bf16 v[32:35], v[172:175], v[208:211], v[32:35]
	v_mfma_f32_16x16x32_bf16 v[20:23], v[164:167], v[234:237], v[20:23]
	v_mfma_f32_16x16x32_bf16 v[16:19], v[172:175], v[234:237], v[16:19]
	v_mfma_f32_16x16x32_bf16 v[4:7], v[164:167], v[242:245], v[4:7]
	v_mfma_f32_16x16x32_bf16 v[0:3], v[172:175], v[242:245], v[0:3]
	s_setprio 0
	s_barrier
	s_add_i32 s51, 0, 0x18000
	s_add_i32 s52, 0, 0x1c000
	v_add_u32_e32 v156, s51, v145
	v_add_u32_e32 v172, s52, v145
	ds_read_b128 v[140:143], v156
	ds_read_b128 v[148:151], v156 offset:1024
	ds_read_b128 v[152:155], v156 offset:2048
	ds_read_b128 v[156:159], v156 offset:3072
	ds_read_b128 v[160:163], v172
	ds_read_b128 v[164:167], v172 offset:1024
	ds_read_b128 v[168:171], v172 offset:2048
	ds_read_b128 v[172:175], v172 offset:3072
	s_add_u32 s16, s22, 0xb0000
	s_addc_u32 s17, s23, 0
	s_mov_b32 m0, s36
	v_lshl_add_u64 v[250:251], s[16:17], 0, v[130:131]
	ds_read_b128 v[176:179], v147 offset:32768
	ds_read_b128 v[180:183], v147 offset:33792
	ds_read_b128 v[184:187], v147 offset:34816
	ds_read_b128 v[208:211], v147 offset:35840
	ds_read_b128 v[230:233], v147 offset:36864
	ds_read_b128 v[234:237], v147 offset:37888
	ds_read_b128 v[238:241], v147 offset:38912
	ds_read_b128 v[242:245], v147 offset:39936
	global_load_lds_dwordx4 v[250:251], off
	v_lshl_add_u64 v[250:251], s[16:17], 0, v[132:133]
	s_mov_b32 m0, s37
	s_nop 0
	global_load_lds_dwordx4 v[250:251], off
	s_waitcnt vmcnt(8)
	s_waitcnt lgkmcnt(0)
	s_barrier
	s_setprio 1
	s_waitcnt lgkmcnt(0)
	v_mfma_f32_16x16x32_bf16 v[126:129], v[140:143], v[176:179], v[126:129]
	v_mfma_f32_16x16x32_bf16 v[122:125], v[152:155], v[176:179], v[122:125]
	v_mfma_f32_16x16x32_bf16 v[108:111], v[140:143], v[184:187], v[108:111]
	v_mfma_f32_16x16x32_bf16 v[104:107], v[152:155], v[184:187], v[104:107]
	v_mfma_f32_16x16x32_bf16 v[92:95], v[140:143], v[230:233], v[92:95]
	v_mfma_f32_16x16x32_bf16 v[88:91], v[152:155], v[230:233], v[88:91]
	v_mfma_f32_16x16x32_bf16 v[76:79], v[140:143], v[238:241], v[76:79]
	v_mfma_f32_16x16x32_bf16 v[72:75], v[152:155], v[238:241], v[72:75]
	v_mfma_f32_16x16x32_bf16 v[126:129], v[148:151], v[180:183], v[126:129]
	v_mfma_f32_16x16x32_bf16 v[122:125], v[156:159], v[180:183], v[122:125]
	v_mfma_f32_16x16x32_bf16 v[108:111], v[148:151], v[208:211], v[108:111]
	v_mfma_f32_16x16x32_bf16 v[104:107], v[156:159], v[208:211], v[104:107]
	v_mfma_f32_16x16x32_bf16 v[92:95], v[148:151], v[234:237], v[92:95]
	v_mfma_f32_16x16x32_bf16 v[88:91], v[156:159], v[234:237], v[88:91]
	v_mfma_f32_16x16x32_bf16 v[76:79], v[148:151], v[242:245], v[76:79]
	v_mfma_f32_16x16x32_bf16 v[72:75], v[156:159], v[242:245], v[72:75]
	s_setprio 0
	s_setprio 1
	v_mfma_f32_16x16x32_bf16 v[118:121], v[160:163], v[176:179], v[118:121]
	v_mfma_f32_16x16x32_bf16 v[114:117], v[168:171], v[176:179], v[114:117]
	v_mfma_f32_16x16x32_bf16 v[100:103], v[160:163], v[184:187], v[100:103]
	v_mfma_f32_16x16x32_bf16 v[96:99], v[168:171], v[184:187], v[96:99]
	v_mfma_f32_16x16x32_bf16 v[84:87], v[160:163], v[230:233], v[84:87]
	v_mfma_f32_16x16x32_bf16 v[80:83], v[168:171], v[230:233], v[80:83]
	v_mfma_f32_16x16x32_bf16 v[68:71], v[160:163], v[238:241], v[68:71]
	v_mfma_f32_16x16x32_bf16 v[64:67], v[168:171], v[238:241], v[64:67]
	v_mfma_f32_16x16x32_bf16 v[118:121], v[164:167], v[180:183], v[118:121]
	v_mfma_f32_16x16x32_bf16 v[114:117], v[172:175], v[180:183], v[114:117]
	v_mfma_f32_16x16x32_bf16 v[100:103], v[164:167], v[208:211], v[100:103]
	v_mfma_f32_16x16x32_bf16 v[96:99], v[172:175], v[208:211], v[96:99]
	v_mfma_f32_16x16x32_bf16 v[84:87], v[164:167], v[234:237], v[84:87]
	v_mfma_f32_16x16x32_bf16 v[80:83], v[172:175], v[234:237], v[80:83]
	v_mfma_f32_16x16x32_bf16 v[68:71], v[164:167], v[242:245], v[68:71]
	v_mfma_f32_16x16x32_bf16 v[64:67], v[172:175], v[242:245], v[64:67]
	s_setprio 0
	s_barrier
	s_add_i32 s16, s51, s30
	v_lshl_add_u64 v[188:189], v[188:189], 0, s[96:97]
	s_mov_b32 m0, s16
	ds_read_b128 v[176:179], v147 offset:49152
	ds_read_b128 v[180:183], v147 offset:50176
	ds_read_b128 v[184:187], v147 offset:51200
	ds_read_b128 v[208:211], v147 offset:52224
	ds_read_b128 v[230:233], v147 offset:53248
	ds_read_b128 v[234:237], v147 offset:54272
	ds_read_b128 v[238:241], v147 offset:55296
	ds_read_b128 v[242:245], v147 offset:56320
	global_load_lds_dwordx4 v[188:189], off
	s_add_i32 m0, s16, 0x2000
	s_add_u32 s16, s20, 0xb0080
	v_lshl_add_u64 v[188:189], v[212:213], 0, s[96:97]
	s_addc_u32 s17, s21, 0
	s_add_i32 s20, s52, s30
	global_load_lds_dwordx4 v[188:189], off
	v_lshl_add_u64 v[188:189], s[16:17], 0, v[112:113]
	s_mov_b32 m0, s20
	s_nop 0
	global_load_lds_dwordx4 v[188:189], off
	v_lshl_add_u64 v[188:189], s[16:17], 0, v[134:135]
	s_add_i32 m0, s20, 0x2000
	s_nop 0
	global_load_lds_dwordx4 v[188:189], off
	v_lshl_add_u64 v[188:189], v[246:247], 0, s[96:97]
	s_mov_b32 m0, s39
	s_nop 0
	global_load_lds_dwordx4 v[188:189], off
	v_lshl_add_u64 v[188:189], v[248:249], 0, s[96:97]
	s_mov_b32 m0, s40
	s_nop 0
	global_load_lds_dwordx4 v[188:189], off
	s_waitcnt vmcnt(8)
	s_waitcnt lgkmcnt(0)
	s_barrier
	s_setprio 1
	s_waitcnt lgkmcnt(0)
	v_mfma_f32_16x16x32_bf16 v[60:63], v[140:143], v[176:179], v[60:63]
	v_mfma_f32_16x16x32_bf16 v[56:59], v[152:155], v[176:179], v[56:59]
	v_mfma_f32_16x16x32_bf16 v[44:47], v[140:143], v[184:187], v[44:47]
	v_mfma_f32_16x16x32_bf16 v[40:43], v[152:155], v[184:187], v[40:43]
	v_mfma_f32_16x16x32_bf16 v[28:31], v[140:143], v[230:233], v[28:31]
	v_mfma_f32_16x16x32_bf16 v[24:27], v[152:155], v[230:233], v[24:27]
	v_mfma_f32_16x16x32_bf16 v[12:15], v[140:143], v[238:241], v[12:15]
	v_mfma_f32_16x16x32_bf16 v[8:11], v[152:155], v[238:241], v[8:11]
	v_mfma_f32_16x16x32_bf16 v[60:63], v[148:151], v[180:183], v[60:63]
	v_mfma_f32_16x16x32_bf16 v[56:59], v[156:159], v[180:183], v[56:59]
	v_mfma_f32_16x16x32_bf16 v[44:47], v[148:151], v[208:211], v[44:47]
	v_mfma_f32_16x16x32_bf16 v[40:43], v[156:159], v[208:211], v[40:43]
	v_mfma_f32_16x16x32_bf16 v[28:31], v[148:151], v[234:237], v[28:31]
	v_mfma_f32_16x16x32_bf16 v[24:27], v[156:159], v[234:237], v[24:27]
	v_mfma_f32_16x16x32_bf16 v[12:15], v[148:151], v[242:245], v[12:15]
	v_mfma_f32_16x16x32_bf16 v[8:11], v[156:159], v[242:245], v[8:11]
	s_setprio 0
	s_setprio 1
	v_mfma_f32_16x16x32_bf16 v[52:55], v[160:163], v[176:179], v[52:55]
	v_mfma_f32_16x16x32_bf16 v[48:51], v[168:171], v[176:179], v[48:51]
	v_mfma_f32_16x16x32_bf16 v[36:39], v[160:163], v[184:187], v[36:39]
	v_mfma_f32_16x16x32_bf16 v[32:35], v[168:171], v[184:187], v[32:35]
	v_mfma_f32_16x16x32_bf16 v[20:23], v[160:163], v[230:233], v[20:23]
	v_mfma_f32_16x16x32_bf16 v[16:19], v[168:171], v[230:233], v[16:19]
	v_mfma_f32_16x16x32_bf16 v[4:7], v[160:163], v[238:241], v[4:7]
	v_mfma_f32_16x16x32_bf16 v[0:3], v[168:171], v[238:241], v[0:3]
	v_mfma_f32_16x16x32_bf16 v[52:55], v[164:167], v[180:183], v[52:55]
	v_mfma_f32_16x16x32_bf16 v[48:51], v[172:175], v[180:183], v[48:51]
	v_mfma_f32_16x16x32_bf16 v[36:39], v[164:167], v[208:211], v[36:39]
	v_mfma_f32_16x16x32_bf16 v[32:35], v[172:175], v[208:211], v[32:35]
	v_mfma_f32_16x16x32_bf16 v[20:23], v[164:167], v[234:237], v[20:23]
	v_mfma_f32_16x16x32_bf16 v[16:19], v[172:175], v[234:237], v[16:19]
	v_mfma_f32_16x16x32_bf16 v[4:7], v[164:167], v[242:245], v[4:7]
	v_mfma_f32_16x16x32_bf16 v[0:3], v[172:175], v[242:245], v[0:3]
	s_setprio 0
	s_barrier
	s_add_i32 s50, s50, 2
	s_add_u32 s48, s48, 0x100
	s_addc_u32 s49, s49, 0
	s_cmp_gt_u32 s50, 41
	s_mov_b64 s[16:17], s[18:19]
	s_cbranch_scc0 .LBB0_1137
	s_branch .Lpeel_exit_1137

.LBB0_1951:
	s_ashr_i32 s17, s16, 31
	s_lshl_b64 s[18:19], s[16:17], 19
	s_add_u32 s18, s42, s18
	s_addc_u32 s19, s43, s19
	s_and_b64 s[20:21], s[2:3], exec
	s_cselect_b32 s5, s19, s27
	s_cselect_b32 s17, s18, s26
	s_ashr_i32 s15, s14, 31
	s_lshl_b64 s[20:21], s[14:15], 19
	s_add_u32 s20, s40, s20
	s_addc_u32 s21, s41, s21
	s_and_b64 s[28:29], s[2:3], exec
	s_cselect_b32 s15, s21, s25
	s_cselect_b32 s51, s20, s24
	s_add_u32 s52, s24, 0x100
	s_addc_u32 s53, s25, 0
	s_add_u32 s24, s26, 0x40080
	s_addc_u32 s25, s27, 0
	s_mov_b32 s54, -2
	s_add_u32 s26, s24, 0xfffc0080
	s_addc_u32 s27, s25, -1
	s_add_i32 s55, 0, 0x10000
	s_cmp_eq_u32 s54, 12
	s_cselect_b32 s29, s5, s27
	s_cselect_b32 s28, s17, s26
	v_add_u32_e32 v144, s55, v146
	s_cselect_b32 s27, s15, s53
	s_cselect_b32 s26, s51, s52
	s_add_i32 s58, 0, 0x14000
	ds_read_b128 v[140:143], v144
	ds_read_b128 v[150:153], v144 offset:1024
	ds_read_b128 v[154:157], v144 offset:2048
	ds_read_b128 v[158:161], v144 offset:3072
	v_add_u32_e32 v144, s58, v146
	ds_read_b128 v[162:165], v144
	ds_read_b128 v[166:169], v144 offset:1024
	ds_read_b128 v[170:173], v144 offset:2048
	ds_read_b128 v[174:177], v144 offset:3072
	v_lshl_add_u64 v[212:213], s[24:25], 0, v[138:139]
	s_add_i32 m0, s23, 0xc000
	ds_read_b128 v[178:181], v149
	ds_read_b128 v[182:185], v149 offset:1024
	ds_read_b128 v[186:189], v149 offset:2048
	ds_read_b128 v[208:211], v149 offset:3072
	ds_read_b128 v[230:233], v149 offset:4096
	ds_read_b128 v[234:237], v149 offset:5120
	ds_read_b128 v[238:241], v149 offset:6144
	ds_read_b128 v[242:245], v149 offset:7168
	global_load_lds_dwordx4 v[212:213], off
	v_lshl_add_u64 v[212:213], s[24:25], 0, v[136:137]
	s_add_i32 m0, s23, 0xe000
	s_nop 0
	global_load_lds_dwordx4 v[212:213], off
	s_waitcnt vmcnt(8)
	s_waitcnt lgkmcnt(0)
	s_barrier
	s_setprio 1
	s_waitcnt lgkmcnt(0)
	v_mfma_f32_16x16x32_bf16 v[126:129], v[140:143], v[178:181], 0
	v_mfma_f32_16x16x32_bf16 v[118:121], v[154:157], v[178:181], 0
	v_mfma_f32_16x16x32_bf16 v[108:111], v[140:143], v[186:189], 0
	v_mfma_f32_16x16x32_bf16 v[100:103], v[154:157], v[186:189], 0
	v_mfma_f32_16x16x32_bf16 v[92:95], v[140:143], v[230:233], 0
	v_mfma_f32_16x16x32_bf16 v[84:87], v[154:157], v[230:233], 0
	v_mfma_f32_16x16x32_bf16 v[76:79], v[140:143], v[238:241], 0
	v_mfma_f32_16x16x32_bf16 v[68:71], v[154:157], v[238:241], 0
	v_mfma_f32_16x16x32_bf16 v[126:129], v[150:153], v[182:185], v[126:129]
	v_mfma_f32_16x16x32_bf16 v[118:121], v[158:161], v[182:185], v[118:121]
	v_mfma_f32_16x16x32_bf16 v[108:111], v[150:153], v[208:211], v[108:111]
	v_mfma_f32_16x16x32_bf16 v[100:103], v[158:161], v[208:211], v[100:103]
	v_mfma_f32_16x16x32_bf16 v[92:95], v[150:153], v[234:237], v[92:95]
	v_mfma_f32_16x16x32_bf16 v[84:87], v[158:161], v[234:237], v[84:87]
	v_mfma_f32_16x16x32_bf16 v[76:79], v[150:153], v[242:245], v[76:79]
	v_mfma_f32_16x16x32_bf16 v[68:71], v[158:161], v[242:245], v[68:71]
	s_setprio 0
	s_setprio 1
	v_mfma_f32_16x16x32_bf16 v[122:125], v[162:165], v[178:181], 0
	v_mfma_f32_16x16x32_bf16 v[114:117], v[170:173], v[178:181], 0
	v_mfma_f32_16x16x32_bf16 v[104:107], v[162:165], v[186:189], 0
	v_mfma_f32_16x16x32_bf16 v[96:99], v[170:173], v[186:189], 0
	v_mfma_f32_16x16x32_bf16 v[88:91], v[162:165], v[230:233], 0
	v_mfma_f32_16x16x32_bf16 v[80:83], v[170:173], v[230:233], 0
	v_mfma_f32_16x16x32_bf16 v[72:75], v[162:165], v[238:241], 0
	v_mfma_f32_16x16x32_bf16 v[64:67], v[170:173], v[238:241], 0
	v_mfma_f32_16x16x32_bf16 v[122:125], v[166:169], v[182:185], v[122:125]
	v_mfma_f32_16x16x32_bf16 v[114:117], v[174:177], v[182:185], v[114:117]
	v_mfma_f32_16x16x32_bf16 v[104:107], v[166:169], v[208:211], v[104:107]
	v_mfma_f32_16x16x32_bf16 v[96:99], v[174:177], v[208:211], v[96:99]
	v_mfma_f32_16x16x32_bf16 v[88:91], v[166:169], v[234:237], v[88:91]
	v_mfma_f32_16x16x32_bf16 v[80:83], v[174:177], v[234:237], v[80:83]
	v_mfma_f32_16x16x32_bf16 v[72:75], v[166:169], v[242:245], v[72:75]
	v_mfma_f32_16x16x32_bf16 v[64:67], v[174:177], v[242:245], v[64:67]
	s_setprio 0
	s_barrier
	s_add_i32 s55, s55, s35
	v_lshl_add_u64 v[212:213], s[26:27], 0, v[112:113]
	s_mov_b32 m0, s55
	ds_read_b128 v[178:181], v149 offset:16384
	ds_read_b128 v[182:185], v149 offset:17408
	ds_read_b128 v[186:189], v149 offset:18432
	ds_read_b128 v[208:211], v149 offset:19456
	ds_read_b128 v[230:233], v149 offset:20480
	ds_read_b128 v[234:237], v149 offset:21504
	ds_read_b128 v[238:241], v149 offset:22528
	ds_read_b128 v[242:245], v149 offset:23552
	global_load_lds_dwordx4 v[212:213], off
	s_add_i32 m0, s55, 0x2000
	s_add_u32 s56, s26, 0x40000
	v_lshl_add_u64 v[246:247], s[26:27], 0, v[134:135]
	s_addc_u32 s57, s27, 0
	s_add_i32 s55, s58, s35
	global_load_lds_dwordx4 v[246:247], off
	v_lshl_add_u64 v[248:249], s[56:57], 0, v[112:113]
	s_mov_b32 m0, s55
	v_lshl_add_u64 v[250:251], s[28:29], 0, v[132:133]
	global_load_lds_dwordx4 v[248:249], off
	v_lshl_add_u64 v[248:249], s[56:57], 0, v[134:135]
	s_add_i32 m0, s55, 0x2000
	s_nop 0
	global_load_lds_dwordx4 v[248:249], off
	v_lshl_add_u64 v[248:249], s[28:29], 0, v[130:131]
	s_mov_b32 m0, s23
	s_nop 0
	global_load_lds_dwordx4 v[248:249], off
	s_mov_b32 m0, s44
	s_nop 0
	global_load_lds_dwordx4 v[250:251], off
	s_waitcnt vmcnt(8)
	s_waitcnt lgkmcnt(0)
	s_barrier
	s_setprio 1
	s_waitcnt lgkmcnt(0)
	v_mfma_f32_16x16x32_bf16 v[60:63], v[140:143], v[178:181], 0
	v_mfma_f32_16x16x32_bf16 v[52:55], v[154:157], v[178:181], 0
	v_mfma_f32_16x16x32_bf16 v[44:47], v[140:143], v[186:189], 0
	v_mfma_f32_16x16x32_bf16 v[36:39], v[154:157], v[186:189], 0
	v_mfma_f32_16x16x32_bf16 v[28:31], v[140:143], v[230:233], 0
	v_mfma_f32_16x16x32_bf16 v[20:23], v[154:157], v[230:233], 0
	v_mfma_f32_16x16x32_bf16 v[12:15], v[140:143], v[238:241], 0
	v_mfma_f32_16x16x32_bf16 v[4:7], v[154:157], v[238:241], 0
	v_mfma_f32_16x16x32_bf16 v[60:63], v[150:153], v[182:185], v[60:63]
	v_mfma_f32_16x16x32_bf16 v[52:55], v[158:161], v[182:185], v[52:55]
	v_mfma_f32_16x16x32_bf16 v[44:47], v[150:153], v[208:211], v[44:47]
	v_mfma_f32_16x16x32_bf16 v[36:39], v[158:161], v[208:211], v[36:39]
	v_mfma_f32_16x16x32_bf16 v[28:31], v[150:153], v[234:237], v[28:31]
	v_mfma_f32_16x16x32_bf16 v[20:23], v[158:161], v[234:237], v[20:23]
	v_mfma_f32_16x16x32_bf16 v[12:15], v[150:153], v[242:245], v[12:15]
	v_mfma_f32_16x16x32_bf16 v[4:7], v[158:161], v[242:245], v[4:7]
	s_setprio 0
	s_setprio 1
	v_mfma_f32_16x16x32_bf16 v[56:59], v[162:165], v[178:181], 0
	v_mfma_f32_16x16x32_bf16 v[48:51], v[170:173], v[178:181], 0
	v_mfma_f32_16x16x32_bf16 v[40:43], v[162:165], v[186:189], 0
	v_mfma_f32_16x16x32_bf16 v[32:35], v[170:173], v[186:189], 0
	v_mfma_f32_16x16x32_bf16 v[24:27], v[162:165], v[230:233], 0
	v_mfma_f32_16x16x32_bf16 v[16:19], v[170:173], v[230:233], 0
	v_mfma_f32_16x16x32_bf16 v[8:11], v[162:165], v[238:241], 0
	v_mfma_f32_16x16x32_bf16 v[0:3], v[170:173], v[238:241], 0
	v_mfma_f32_16x16x32_bf16 v[56:59], v[166:169], v[182:185], v[56:59]
	v_mfma_f32_16x16x32_bf16 v[48:51], v[174:177], v[182:185], v[48:51]
	v_mfma_f32_16x16x32_bf16 v[40:43], v[166:169], v[208:211], v[40:43]
	v_mfma_f32_16x16x32_bf16 v[32:35], v[174:177], v[208:211], v[32:35]
	v_mfma_f32_16x16x32_bf16 v[24:27], v[166:169], v[234:237], v[24:27]
	v_mfma_f32_16x16x32_bf16 v[16:19], v[174:177], v[234:237], v[16:19]
	v_mfma_f32_16x16x32_bf16 v[8:11], v[166:169], v[242:245], v[8:11]
	v_mfma_f32_16x16x32_bf16 v[0:3], v[174:177], v[242:245], v[0:3]
	s_setprio 0
	s_barrier
	s_add_i32 s55, 0, 0x18000
	v_add_u32_e32 v144, s55, v146
	s_add_i32 s56, 0, 0x1c000
	ds_read_b128 v[140:143], v144
	ds_read_b128 v[150:153], v144 offset:1024
	ds_read_b128 v[154:157], v144 offset:2048
	ds_read_b128 v[158:161], v144 offset:3072
	v_add_u32_e32 v144, s56, v146
	ds_read_b128 v[162:165], v144
	ds_read_b128 v[166:169], v144 offset:1024
	ds_read_b128 v[170:173], v144 offset:2048
	ds_read_b128 v[174:177], v144 offset:3072
	s_add_u32 s28, s28, 0x40000
	s_addc_u32 s29, s29, 0
	s_mov_b32 m0, s45
	v_lshl_add_u64 v[252:253], s[28:29], 0, v[130:131]
	ds_read_b128 v[178:181], v149 offset:32768
	ds_read_b128 v[182:185], v149 offset:33792
	ds_read_b128 v[186:189], v149 offset:34816
	ds_read_b128 v[208:211], v149 offset:35840
	ds_read_b128 v[230:233], v149 offset:36864
	ds_read_b128 v[234:237], v149 offset:37888
	ds_read_b128 v[238:241], v149 offset:38912
	ds_read_b128 v[242:245], v149 offset:39936
	global_load_lds_dwordx4 v[252:253], off
	v_lshl_add_u64 v[252:253], s[28:29], 0, v[132:133]
	s_mov_b32 m0, s46
	s_nop 0
	global_load_lds_dwordx4 v[252:253], off
	s_waitcnt vmcnt(8)
	s_waitcnt lgkmcnt(0)
	s_barrier
	s_setprio 1
	s_waitcnt lgkmcnt(0)
	v_mfma_f32_16x16x32_bf16 v[126:129], v[140:143], v[178:181], v[126:129]
	v_mfma_f32_16x16x32_bf16 v[118:121], v[154:157], v[178:181], v[118:121]
	v_mfma_f32_16x16x32_bf16 v[108:111], v[140:143], v[186:189], v[108:111]
	v_mfma_f32_16x16x32_bf16 v[100:103], v[154:157], v[186:189], v[100:103]
	v_mfma_f32_16x16x32_bf16 v[92:95], v[140:143], v[230:233], v[92:95]
	v_mfma_f32_16x16x32_bf16 v[84:87], v[154:157], v[230:233], v[84:87]
	v_mfma_f32_16x16x32_bf16 v[76:79], v[140:143], v[238:241], v[76:79]
	v_mfma_f32_16x16x32_bf16 v[68:71], v[154:157], v[238:241], v[68:71]
	v_mfma_f32_16x16x32_bf16 v[126:129], v[150:153], v[182:185], v[126:129]
	v_mfma_f32_16x16x32_bf16 v[118:121], v[158:161], v[182:185], v[118:121]
	v_mfma_f32_16x16x32_bf16 v[108:111], v[150:153], v[208:211], v[108:111]
	v_mfma_f32_16x16x32_bf16 v[100:103], v[158:161], v[208:211], v[100:103]
	v_mfma_f32_16x16x32_bf16 v[92:95], v[150:153], v[234:237], v[92:95]
	v_mfma_f32_16x16x32_bf16 v[84:87], v[158:161], v[234:237], v[84:87]
	v_mfma_f32_16x16x32_bf16 v[76:79], v[150:153], v[242:245], v[76:79]
	v_mfma_f32_16x16x32_bf16 v[68:71], v[158:161], v[242:245], v[68:71]
	s_setprio 0
	s_setprio 1
	v_mfma_f32_16x16x32_bf16 v[122:125], v[162:165], v[178:181], v[122:125]
	v_mfma_f32_16x16x32_bf16 v[114:117], v[170:173], v[178:181], v[114:117]
	v_mfma_f32_16x16x32_bf16 v[104:107], v[162:165], v[186:189], v[104:107]
	v_mfma_f32_16x16x32_bf16 v[96:99], v[170:173], v[186:189], v[96:99]
	v_mfma_f32_16x16x32_bf16 v[88:91], v[162:165], v[230:233], v[88:91]
	v_mfma_f32_16x16x32_bf16 v[80:83], v[170:173], v[230:233], v[80:83]
	v_mfma_f32_16x16x32_bf16 v[72:75], v[162:165], v[238:241], v[72:75]
	v_mfma_f32_16x16x32_bf16 v[64:67], v[170:173], v[238:241], v[64:67]
	v_mfma_f32_16x16x32_bf16 v[122:125], v[166:169], v[182:185], v[122:125]
	v_mfma_f32_16x16x32_bf16 v[114:117], v[174:177], v[182:185], v[114:117]
	v_mfma_f32_16x16x32_bf16 v[104:107], v[166:169], v[208:211], v[104:107]
	v_mfma_f32_16x16x32_bf16 v[96:99], v[174:177], v[208:211], v[96:99]
	v_mfma_f32_16x16x32_bf16 v[88:91], v[166:169], v[234:237], v[88:91]
	v_mfma_f32_16x16x32_bf16 v[80:83], v[174:177], v[234:237], v[80:83]
	v_mfma_f32_16x16x32_bf16 v[72:75], v[166:169], v[242:245], v[72:75]
	v_mfma_f32_16x16x32_bf16 v[64:67], v[174:177], v[242:245], v[64:67]
	s_setprio 0
	s_barrier
	s_add_i32 s28, s55, s35
	v_lshl_add_u64 v[212:213], v[212:213], 0, s[96:97]
	s_mov_b32 m0, s28
	ds_read_b128 v[178:181], v149 offset:49152
	ds_read_b128 v[182:185], v149 offset:50176
	ds_read_b128 v[186:189], v149 offset:51200
	ds_read_b128 v[208:211], v149 offset:52224
	ds_read_b128 v[230:233], v149 offset:53248
	ds_read_b128 v[234:237], v149 offset:54272
	ds_read_b128 v[238:241], v149 offset:55296
	ds_read_b128 v[242:245], v149 offset:56320
	global_load_lds_dwordx4 v[212:213], off
	s_add_i32 m0, s28, 0x2000
	s_add_u32 s26, s26, 0x40080
	v_lshl_add_u64 v[212:213], v[246:247], 0, s[96:97]
	s_addc_u32 s27, s27, 0
	s_add_i32 s28, s56, s35
	global_load_lds_dwordx4 v[212:213], off
	v_lshl_add_u64 v[212:213], s[26:27], 0, v[112:113]
	s_mov_b32 m0, s28
	s_nop 0
	global_load_lds_dwordx4 v[212:213], off
	v_lshl_add_u64 v[212:213], s[26:27], 0, v[134:135]
	s_add_i32 m0, s28, 0x2000
	s_nop 0
	global_load_lds_dwordx4 v[212:213], off
	v_lshl_add_u64 v[212:213], v[248:249], 0, s[96:97]
	s_mov_b32 m0, s47
	s_nop 0
	global_load_lds_dwordx4 v[212:213], off
	v_lshl_add_u64 v[212:213], v[250:251], 0, s[96:97]
	s_mov_b32 m0, s48
	s_nop 0
	global_load_lds_dwordx4 v[212:213], off
	s_waitcnt vmcnt(8)
	s_waitcnt lgkmcnt(0)
	s_barrier
	s_setprio 1
	s_waitcnt lgkmcnt(0)
	v_mfma_f32_16x16x32_bf16 v[60:63], v[140:143], v[178:181], v[60:63]
	v_mfma_f32_16x16x32_bf16 v[52:55], v[154:157], v[178:181], v[52:55]
	v_mfma_f32_16x16x32_bf16 v[44:47], v[140:143], v[186:189], v[44:47]
	v_mfma_f32_16x16x32_bf16 v[36:39], v[154:157], v[186:189], v[36:39]
	v_mfma_f32_16x16x32_bf16 v[28:31], v[140:143], v[230:233], v[28:31]
	v_mfma_f32_16x16x32_bf16 v[20:23], v[154:157], v[230:233], v[20:23]
	v_mfma_f32_16x16x32_bf16 v[12:15], v[140:143], v[238:241], v[12:15]
	v_mfma_f32_16x16x32_bf16 v[4:7], v[154:157], v[238:241], v[4:7]
	v_mfma_f32_16x16x32_bf16 v[60:63], v[150:153], v[182:185], v[60:63]
	v_mfma_f32_16x16x32_bf16 v[52:55], v[158:161], v[182:185], v[52:55]
	v_mfma_f32_16x16x32_bf16 v[44:47], v[150:153], v[208:211], v[44:47]
	v_mfma_f32_16x16x32_bf16 v[36:39], v[158:161], v[208:211], v[36:39]
	v_mfma_f32_16x16x32_bf16 v[28:31], v[150:153], v[234:237], v[28:31]
	v_mfma_f32_16x16x32_bf16 v[20:23], v[158:161], v[234:237], v[20:23]
	v_mfma_f32_16x16x32_bf16 v[12:15], v[150:153], v[242:245], v[12:15]
	v_mfma_f32_16x16x32_bf16 v[4:7], v[158:161], v[242:245], v[4:7]
	s_setprio 0
	s_setprio 1
	v_mfma_f32_16x16x32_bf16 v[56:59], v[162:165], v[178:181], v[56:59]
	v_mfma_f32_16x16x32_bf16 v[48:51], v[170:173], v[178:181], v[48:51]
	v_mfma_f32_16x16x32_bf16 v[40:43], v[162:165], v[186:189], v[40:43]
	v_mfma_f32_16x16x32_bf16 v[32:35], v[170:173], v[186:189], v[32:35]
	v_mfma_f32_16x16x32_bf16 v[24:27], v[162:165], v[230:233], v[24:27]
	v_mfma_f32_16x16x32_bf16 v[16:19], v[170:173], v[230:233], v[16:19]
	v_mfma_f32_16x16x32_bf16 v[8:11], v[162:165], v[238:241], v[8:11]
	v_mfma_f32_16x16x32_bf16 v[0:3], v[170:173], v[238:241], v[0:3]
	v_mfma_f32_16x16x32_bf16 v[56:59], v[166:169], v[182:185], v[56:59]
	v_mfma_f32_16x16x32_bf16 v[48:51], v[174:177], v[182:185], v[48:51]
	v_mfma_f32_16x16x32_bf16 v[40:43], v[166:169], v[208:211], v[40:43]
	v_mfma_f32_16x16x32_bf16 v[32:35], v[174:177], v[208:211], v[32:35]
	v_mfma_f32_16x16x32_bf16 v[24:27], v[166:169], v[234:237], v[24:27]
	v_mfma_f32_16x16x32_bf16 v[16:19], v[174:177], v[234:237], v[16:19]
	v_mfma_f32_16x16x32_bf16 v[8:11], v[166:169], v[242:245], v[8:11]
	v_mfma_f32_16x16x32_bf16 v[0:3], v[174:177], v[242:245], v[0:3]
	s_setprio 0
	s_barrier
	s_add_i32 s54, s54, 2
	s_add_u32 s52, s52, 0x100
	s_addc_u32 s53, s53, 0
	s_add_u32 s24, s24, 0x100
	s_addc_u32 s25, s25, 0
	s_cmp_gt_u32 s54, 13
	s_cbranch_scc0 .LBB0_1952
	s_branch .Lpeel_exit_1952

.LBB0_2150:
	s_ashr_i32 s29, s28, 31
	s_lshl_b64 s[30:31], s[28:29], 19
	s_add_u32 s30, s49, s30
	s_addc_u32 s31, s50, s31
	s_and_b64 s[40:41], s[6:7], exec
	s_cselect_b32 s11, s31, s39
	s_cselect_b32 s29, s30, s38
	s_ashr_i32 s27, s26, 31
	s_lshl_b64 s[40:41], s[26:27], 19
	s_add_u32 s46, s51, s40
	s_addc_u32 s47, s52, s41
	s_and_b64 s[40:41], s[6:7], exec
	s_cselect_b32 s27, s47, s9
	s_cselect_b32 s35, s46, s8
	s_add_u32 s42, s8, 0x100
	s_addc_u32 s43, s9, 0
	s_add_u32 s8, s38, 0x40080
	s_addc_u32 s9, s39, 0
	s_mov_b32 s44, -2
	s_add_u32 s38, s8, 0xfffc0080
	s_addc_u32 s39, s9, -1
	s_add_i32 s45, 0, 0x10000
	s_cmp_eq_u32 s44, 12
	s_cselect_b32 s41, s11, s39
	s_cselect_b32 s40, s29, s38
	v_add_u32_e32 v112, s45, v169
	s_cselect_b32 s39, s27, s43
	s_cselect_b32 s38, s35, s42
	s_add_i32 s68, 0, 0x14000
	ds_read_b128 v[130:133], v112
	ds_read_b128 v[134:137], v112 offset:1024
	ds_read_b128 v[150:153], v112 offset:2048
	ds_read_b128 v[154:157], v112 offset:3072
	v_add_u32_e32 v112, s68, v169
	ds_read_b128 v[158:161], v112
	ds_read_b128 v[162:165], v112 offset:1024
	ds_read_b128 v[174:177], v112 offset:2048
	ds_read_b128 v[178:181], v112 offset:3072
	v_lshl_add_u64 v[166:167], s[8:9], 0, v[148:149]
	s_add_i32 m0, s37, 0xc000
	ds_read_b128 v[182:185], v172
	ds_read_b128 v[186:189], v172 offset:1024
	ds_read_b128 v[208:211], v172 offset:2048
	ds_read_b128 v[230:233], v172 offset:3072
	ds_read_b128 v[234:237], v172 offset:4096
	ds_read_b128 v[238:241], v172 offset:5120
	ds_read_b128 v[242:245], v172 offset:6144
	ds_read_b128 v[246:249], v172 offset:7168
	global_load_lds_dwordx4 v[166:167], off
	v_lshl_add_u64 v[166:167], s[8:9], 0, v[146:147]
	s_add_i32 m0, s37, 0xe000
	s_nop 0
	global_load_lds_dwordx4 v[166:167], off
	s_waitcnt vmcnt(8)
	s_waitcnt lgkmcnt(0)
	s_barrier
	s_setprio 1
	s_waitcnt lgkmcnt(0)
	v_mfma_f32_16x16x32_bf16 v[126:129], v[130:133], v[182:185], 0
	v_mfma_f32_16x16x32_bf16 v[122:125], v[150:153], v[182:185], 0
	v_mfma_f32_16x16x32_bf16 v[108:111], v[130:133], v[208:211], 0
	v_mfma_f32_16x16x32_bf16 v[104:107], v[150:153], v[208:211], 0
	v_mfma_f32_16x16x32_bf16 v[92:95], v[130:133], v[234:237], 0
	v_mfma_f32_16x16x32_bf16 v[88:91], v[150:153], v[234:237], 0
	v_mfma_f32_16x16x32_bf16 v[76:79], v[130:133], v[242:245], 0
	v_mfma_f32_16x16x32_bf16 v[72:75], v[150:153], v[242:245], 0
	v_mfma_f32_16x16x32_bf16 v[126:129], v[134:137], v[186:189], v[126:129]
	v_mfma_f32_16x16x32_bf16 v[122:125], v[154:157], v[186:189], v[122:125]
	v_mfma_f32_16x16x32_bf16 v[108:111], v[134:137], v[230:233], v[108:111]
	v_mfma_f32_16x16x32_bf16 v[104:107], v[154:157], v[230:233], v[104:107]
	v_mfma_f32_16x16x32_bf16 v[92:95], v[134:137], v[238:241], v[92:95]
	v_mfma_f32_16x16x32_bf16 v[88:91], v[154:157], v[238:241], v[88:91]
	v_mfma_f32_16x16x32_bf16 v[76:79], v[134:137], v[246:249], v[76:79]
	v_mfma_f32_16x16x32_bf16 v[72:75], v[154:157], v[246:249], v[72:75]
	s_setprio 0
	s_setprio 1
	v_mfma_f32_16x16x32_bf16 v[118:121], v[158:161], v[182:185], 0
	v_mfma_f32_16x16x32_bf16 v[114:117], v[174:177], v[182:185], 0
	v_mfma_f32_16x16x32_bf16 v[100:103], v[158:161], v[208:211], 0
	v_mfma_f32_16x16x32_bf16 v[96:99], v[174:177], v[208:211], 0
	v_mfma_f32_16x16x32_bf16 v[84:87], v[158:161], v[234:237], 0
	v_mfma_f32_16x16x32_bf16 v[80:83], v[174:177], v[234:237], 0
	v_mfma_f32_16x16x32_bf16 v[68:71], v[158:161], v[242:245], 0
	v_mfma_f32_16x16x32_bf16 v[64:67], v[174:177], v[242:245], 0
	v_mfma_f32_16x16x32_bf16 v[118:121], v[162:165], v[186:189], v[118:121]
	v_mfma_f32_16x16x32_bf16 v[114:117], v[178:181], v[186:189], v[114:117]
	v_mfma_f32_16x16x32_bf16 v[100:103], v[162:165], v[230:233], v[100:103]
	v_mfma_f32_16x16x32_bf16 v[96:99], v[178:181], v[230:233], v[96:99]
	v_mfma_f32_16x16x32_bf16 v[84:87], v[162:165], v[238:241], v[84:87]
	v_mfma_f32_16x16x32_bf16 v[80:83], v[178:181], v[238:241], v[80:83]
	v_mfma_f32_16x16x32_bf16 v[68:71], v[162:165], v[246:249], v[68:71]
	v_mfma_f32_16x16x32_bf16 v[64:67], v[178:181], v[246:249], v[64:67]
	s_setprio 0
	s_barrier
	s_add_i32 s45, s45, s58
	v_lshl_add_u64 v[166:167], s[38:39], 0, v[140:141]
	s_mov_b32 m0, s45
	ds_read_b128 v[182:185], v172 offset:16384
	ds_read_b128 v[186:189], v172 offset:17408
	ds_read_b128 v[208:211], v172 offset:18432
	ds_read_b128 v[230:233], v172 offset:19456
	ds_read_b128 v[234:237], v172 offset:20480
	ds_read_b128 v[238:241], v172 offset:21504
	ds_read_b128 v[242:245], v172 offset:22528
	ds_read_b128 v[246:249], v172 offset:23552
	global_load_lds_dwordx4 v[166:167], off
	s_add_i32 m0, s45, 0x2000
	s_add_u32 s66, s38, 0x40000
	v_lshl_add_u64 v[212:213], s[38:39], 0, v[144:145]
	s_addc_u32 s67, s39, 0
	s_add_i32 s45, s68, s58
	global_load_lds_dwordx4 v[212:213], off
	v_lshl_add_u64 v[228:229], s[66:67], 0, v[140:141]
	s_mov_b32 m0, s45
	v_lshl_add_u64 v[250:251], s[40:41], 0, v[142:143]
	global_load_lds_dwordx4 v[228:229], off
	v_lshl_add_u64 v[228:229], s[66:67], 0, v[144:145]
	s_add_i32 m0, s45, 0x2000
	s_nop 0
	global_load_lds_dwordx4 v[228:229], off
	v_lshl_add_u64 v[228:229], s[40:41], 0, v[138:139]
	s_mov_b32 m0, s37
	s_nop 0
	global_load_lds_dwordx4 v[228:229], off
	s_mov_b32 m0, s59
	s_nop 0
	global_load_lds_dwordx4 v[250:251], off
	s_waitcnt vmcnt(8)
	s_waitcnt lgkmcnt(0)
	s_barrier
	s_setprio 1
	s_waitcnt lgkmcnt(0)
	v_mfma_f32_16x16x32_bf16 v[60:63], v[130:133], v[182:185], 0
	v_mfma_f32_16x16x32_bf16 v[56:59], v[150:153], v[182:185], 0
	v_mfma_f32_16x16x32_bf16 v[44:47], v[130:133], v[208:211], 0
	v_mfma_f32_16x16x32_bf16 v[40:43], v[150:153], v[208:211], 0
	v_mfma_f32_16x16x32_bf16 v[28:31], v[130:133], v[234:237], 0
	v_mfma_f32_16x16x32_bf16 v[24:27], v[150:153], v[234:237], 0
	v_mfma_f32_16x16x32_bf16 v[12:15], v[130:133], v[242:245], 0
	v_mfma_f32_16x16x32_bf16 v[8:11], v[150:153], v[242:245], 0
	v_mfma_f32_16x16x32_bf16 v[60:63], v[134:137], v[186:189], v[60:63]
	v_mfma_f32_16x16x32_bf16 v[56:59], v[154:157], v[186:189], v[56:59]
	v_mfma_f32_16x16x32_bf16 v[44:47], v[134:137], v[230:233], v[44:47]
	v_mfma_f32_16x16x32_bf16 v[40:43], v[154:157], v[230:233], v[40:43]
	v_mfma_f32_16x16x32_bf16 v[28:31], v[134:137], v[238:241], v[28:31]
	v_mfma_f32_16x16x32_bf16 v[24:27], v[154:157], v[238:241], v[24:27]
	v_mfma_f32_16x16x32_bf16 v[12:15], v[134:137], v[246:249], v[12:15]
	v_mfma_f32_16x16x32_bf16 v[8:11], v[154:157], v[246:249], v[8:11]
	s_setprio 0
	s_setprio 1
	v_mfma_f32_16x16x32_bf16 v[52:55], v[158:161], v[182:185], 0
	v_mfma_f32_16x16x32_bf16 v[48:51], v[174:177], v[182:185], 0
	v_mfma_f32_16x16x32_bf16 v[36:39], v[158:161], v[208:211], 0
	v_mfma_f32_16x16x32_bf16 v[32:35], v[174:177], v[208:211], 0
	v_mfma_f32_16x16x32_bf16 v[20:23], v[158:161], v[234:237], 0
	v_mfma_f32_16x16x32_bf16 v[16:19], v[174:177], v[234:237], 0
	v_mfma_f32_16x16x32_bf16 v[4:7], v[158:161], v[242:245], 0
	v_mfma_f32_16x16x32_bf16 v[0:3], v[174:177], v[242:245], 0
	v_mfma_f32_16x16x32_bf16 v[52:55], v[162:165], v[186:189], v[52:55]
	v_mfma_f32_16x16x32_bf16 v[48:51], v[178:181], v[186:189], v[48:51]
	v_mfma_f32_16x16x32_bf16 v[36:39], v[162:165], v[230:233], v[36:39]
	v_mfma_f32_16x16x32_bf16 v[32:35], v[178:181], v[230:233], v[32:35]
	v_mfma_f32_16x16x32_bf16 v[20:23], v[162:165], v[238:241], v[20:23]
	v_mfma_f32_16x16x32_bf16 v[16:19], v[178:181], v[238:241], v[16:19]
	v_mfma_f32_16x16x32_bf16 v[4:7], v[162:165], v[246:249], v[4:7]
	v_mfma_f32_16x16x32_bf16 v[0:3], v[178:181], v[246:249], v[0:3]
	s_setprio 0
	s_barrier
	s_add_i32 s45, 0, 0x18000
	v_add_u32_e32 v112, s45, v169
	s_add_i32 s66, 0, 0x1c000
	ds_read_b128 v[130:133], v112
	ds_read_b128 v[134:137], v112 offset:1024
	ds_read_b128 v[150:153], v112 offset:2048
	ds_read_b128 v[154:157], v112 offset:3072
	v_add_u32_e32 v112, s66, v169
	ds_read_b128 v[158:161], v112
	ds_read_b128 v[162:165], v112 offset:1024
	ds_read_b128 v[174:177], v112 offset:2048
	ds_read_b128 v[178:181], v112 offset:3072
	s_add_u32 s40, s40, 0x40000
	s_addc_u32 s41, s41, 0
	s_mov_b32 m0, s60
	v_lshl_add_u64 v[252:253], s[40:41], 0, v[138:139]
	ds_read_b128 v[182:185], v172 offset:32768
	ds_read_b128 v[186:189], v172 offset:33792
	ds_read_b128 v[208:211], v172 offset:34816
	ds_read_b128 v[230:233], v172 offset:35840
	ds_read_b128 v[234:237], v172 offset:36864
	ds_read_b128 v[238:241], v172 offset:37888
	ds_read_b128 v[242:245], v172 offset:38912
	ds_read_b128 v[246:249], v172 offset:39936
	global_load_lds_dwordx4 v[252:253], off
	v_lshl_add_u64 v[252:253], s[40:41], 0, v[142:143]
	s_mov_b32 m0, s61
	s_nop 0
	global_load_lds_dwordx4 v[252:253], off
	s_waitcnt vmcnt(8)
	s_waitcnt lgkmcnt(0)
	s_barrier
	s_setprio 1
	s_waitcnt lgkmcnt(0)
	v_mfma_f32_16x16x32_bf16 v[126:129], v[130:133], v[182:185], v[126:129]
	v_mfma_f32_16x16x32_bf16 v[122:125], v[150:153], v[182:185], v[122:125]
	v_mfma_f32_16x16x32_bf16 v[108:111], v[130:133], v[208:211], v[108:111]
	v_mfma_f32_16x16x32_bf16 v[104:107], v[150:153], v[208:211], v[104:107]
	v_mfma_f32_16x16x32_bf16 v[92:95], v[130:133], v[234:237], v[92:95]
	v_mfma_f32_16x16x32_bf16 v[88:91], v[150:153], v[234:237], v[88:91]
	v_mfma_f32_16x16x32_bf16 v[76:79], v[130:133], v[242:245], v[76:79]
	v_mfma_f32_16x16x32_bf16 v[72:75], v[150:153], v[242:245], v[72:75]
	v_mfma_f32_16x16x32_bf16 v[126:129], v[134:137], v[186:189], v[126:129]
	v_mfma_f32_16x16x32_bf16 v[122:125], v[154:157], v[186:189], v[122:125]
	v_mfma_f32_16x16x32_bf16 v[108:111], v[134:137], v[230:233], v[108:111]
	v_mfma_f32_16x16x32_bf16 v[104:107], v[154:157], v[230:233], v[104:107]
	v_mfma_f32_16x16x32_bf16 v[92:95], v[134:137], v[238:241], v[92:95]
	v_mfma_f32_16x16x32_bf16 v[88:91], v[154:157], v[238:241], v[88:91]
	v_mfma_f32_16x16x32_bf16 v[76:79], v[134:137], v[246:249], v[76:79]
	v_mfma_f32_16x16x32_bf16 v[72:75], v[154:157], v[246:249], v[72:75]
	s_setprio 0
	s_setprio 1
	v_mfma_f32_16x16x32_bf16 v[118:121], v[158:161], v[182:185], v[118:121]
	v_mfma_f32_16x16x32_bf16 v[114:117], v[174:177], v[182:185], v[114:117]
	v_mfma_f32_16x16x32_bf16 v[100:103], v[158:161], v[208:211], v[100:103]
	v_mfma_f32_16x16x32_bf16 v[96:99], v[174:177], v[208:211], v[96:99]
	v_mfma_f32_16x16x32_bf16 v[84:87], v[158:161], v[234:237], v[84:87]
	v_mfma_f32_16x16x32_bf16 v[80:83], v[174:177], v[234:237], v[80:83]
	v_mfma_f32_16x16x32_bf16 v[68:71], v[158:161], v[242:245], v[68:71]
	v_mfma_f32_16x16x32_bf16 v[64:67], v[174:177], v[242:245], v[64:67]
	v_mfma_f32_16x16x32_bf16 v[118:121], v[162:165], v[186:189], v[118:121]
	v_mfma_f32_16x16x32_bf16 v[114:117], v[178:181], v[186:189], v[114:117]
	v_mfma_f32_16x16x32_bf16 v[100:103], v[162:165], v[230:233], v[100:103]
	v_mfma_f32_16x16x32_bf16 v[96:99], v[178:181], v[230:233], v[96:99]
	v_mfma_f32_16x16x32_bf16 v[84:87], v[162:165], v[238:241], v[84:87]
	v_mfma_f32_16x16x32_bf16 v[80:83], v[178:181], v[238:241], v[80:83]
	v_mfma_f32_16x16x32_bf16 v[68:71], v[162:165], v[246:249], v[68:71]
	v_mfma_f32_16x16x32_bf16 v[64:67], v[178:181], v[246:249], v[64:67]
	s_setprio 0
	s_barrier
	s_add_i32 s40, s45, s58
	v_lshl_add_u64 v[166:167], v[166:167], 0, s[96:97]
	s_mov_b32 m0, s40
	ds_read_b128 v[182:185], v172 offset:49152
	ds_read_b128 v[186:189], v172 offset:50176
	ds_read_b128 v[208:211], v172 offset:51200
	ds_read_b128 v[230:233], v172 offset:52224
	ds_read_b128 v[234:237], v172 offset:53248
	ds_read_b128 v[238:241], v172 offset:54272
	ds_read_b128 v[242:245], v172 offset:55296
	ds_read_b128 v[246:249], v172 offset:56320
	global_load_lds_dwordx4 v[166:167], off
	s_add_i32 m0, s40, 0x2000
	s_add_u32 s38, s38, 0x40080
	v_lshl_add_u64 v[166:167], v[212:213], 0, s[96:97]
	s_addc_u32 s39, s39, 0
	s_add_i32 s40, s66, s58
	global_load_lds_dwordx4 v[166:167], off
	v_lshl_add_u64 v[166:167], s[38:39], 0, v[140:141]
	s_mov_b32 m0, s40
	s_nop 0
	global_load_lds_dwordx4 v[166:167], off
	v_lshl_add_u64 v[166:167], s[38:39], 0, v[144:145]
	s_add_i32 m0, s40, 0x2000
	s_nop 0
	global_load_lds_dwordx4 v[166:167], off
	v_lshl_add_u64 v[166:167], v[228:229], 0, s[96:97]
	s_mov_b32 m0, s62
	s_nop 0
	global_load_lds_dwordx4 v[166:167], off
	v_lshl_add_u64 v[166:167], v[250:251], 0, s[96:97]
	s_mov_b32 m0, s63
	s_nop 0
	global_load_lds_dwordx4 v[166:167], off
	s_waitcnt vmcnt(8)
	s_waitcnt lgkmcnt(0)
	s_barrier
	s_setprio 1
	s_waitcnt lgkmcnt(0)
	v_mfma_f32_16x16x32_bf16 v[60:63], v[130:133], v[182:185], v[60:63]
	v_mfma_f32_16x16x32_bf16 v[56:59], v[150:153], v[182:185], v[56:59]
	v_mfma_f32_16x16x32_bf16 v[44:47], v[130:133], v[208:211], v[44:47]
	v_mfma_f32_16x16x32_bf16 v[40:43], v[150:153], v[208:211], v[40:43]
	v_mfma_f32_16x16x32_bf16 v[28:31], v[130:133], v[234:237], v[28:31]
	v_mfma_f32_16x16x32_bf16 v[24:27], v[150:153], v[234:237], v[24:27]
	v_mfma_f32_16x16x32_bf16 v[12:15], v[130:133], v[242:245], v[12:15]
	v_mfma_f32_16x16x32_bf16 v[8:11], v[150:153], v[242:245], v[8:11]
	v_mfma_f32_16x16x32_bf16 v[60:63], v[134:137], v[186:189], v[60:63]
	v_mfma_f32_16x16x32_bf16 v[56:59], v[154:157], v[186:189], v[56:59]
	v_mfma_f32_16x16x32_bf16 v[44:47], v[134:137], v[230:233], v[44:47]
	v_mfma_f32_16x16x32_bf16 v[40:43], v[154:157], v[230:233], v[40:43]
	v_mfma_f32_16x16x32_bf16 v[28:31], v[134:137], v[238:241], v[28:31]
	v_mfma_f32_16x16x32_bf16 v[24:27], v[154:157], v[238:241], v[24:27]
	v_mfma_f32_16x16x32_bf16 v[12:15], v[134:137], v[246:249], v[12:15]
	v_mfma_f32_16x16x32_bf16 v[8:11], v[154:157], v[246:249], v[8:11]
	s_setprio 0
	s_setprio 1
	v_mfma_f32_16x16x32_bf16 v[52:55], v[158:161], v[182:185], v[52:55]
	v_mfma_f32_16x16x32_bf16 v[48:51], v[174:177], v[182:185], v[48:51]
	v_mfma_f32_16x16x32_bf16 v[36:39], v[158:161], v[208:211], v[36:39]
	v_mfma_f32_16x16x32_bf16 v[32:35], v[174:177], v[208:211], v[32:35]
	v_mfma_f32_16x16x32_bf16 v[20:23], v[158:161], v[234:237], v[20:23]
	v_mfma_f32_16x16x32_bf16 v[16:19], v[174:177], v[234:237], v[16:19]
	v_mfma_f32_16x16x32_bf16 v[4:7], v[158:161], v[242:245], v[4:7]
	v_mfma_f32_16x16x32_bf16 v[0:3], v[174:177], v[242:245], v[0:3]
	v_mfma_f32_16x16x32_bf16 v[52:55], v[162:165], v[186:189], v[52:55]
	v_mfma_f32_16x16x32_bf16 v[48:51], v[178:181], v[186:189], v[48:51]
	v_mfma_f32_16x16x32_bf16 v[36:39], v[162:165], v[230:233], v[36:39]
	v_mfma_f32_16x16x32_bf16 v[32:35], v[178:181], v[230:233], v[32:35]
	v_mfma_f32_16x16x32_bf16 v[20:23], v[162:165], v[238:241], v[20:23]
	v_mfma_f32_16x16x32_bf16 v[16:19], v[178:181], v[238:241], v[16:19]
	v_mfma_f32_16x16x32_bf16 v[4:7], v[162:165], v[246:249], v[4:7]
	v_mfma_f32_16x16x32_bf16 v[0:3], v[178:181], v[246:249], v[0:3]
	s_setprio 0
	s_barrier
	s_add_i32 s44, s44, 2
	s_add_u32 s42, s42, 0x100
	s_addc_u32 s43, s43, 0
	s_add_u32 s8, s8, 0x100
	s_addc_u32 s9, s9, 0
	s_cmp_gt_u32 s44, 13
	s_cbranch_scc0 .LBB0_2151
	s_branch .Lpeel_exit_2151

.Lpeel_exit_2151:
	s_and_b64 vcc, exec, s[22:23]
	s_cbranch_vccz .LBB0_2154
	s_barrier

.LBB0_2368:
	s_ashr_i32 s23, s22, 31
	s_lshl_b64 s[24:25], s[22:23], 19
	s_add_u32 s24, s49, s24
	s_addc_u32 s25, s50, s25
	s_and_b64 s[26:27], s[2:3], exec
	s_cselect_b32 s5, s25, s29
	s_cselect_b32 s23, s24, s28
	s_ashr_i32 s15, s14, 31
	s_lshl_b64 s[26:27], s[14:15], 19
	s_add_u32 s26, s51, s26
	s_addc_u32 s27, s52, s27
	s_and_b64 s[30:31], s[2:3], exec
	s_cselect_b32 s15, s27, s7
	s_cselect_b32 s47, s26, s6
	s_add_u32 s54, s6, 0x100
	s_addc_u32 s55, s7, 0
	s_add_u32 s6, s28, 0x40080
	s_addc_u32 s7, s29, 0
	s_mov_b32 s56, -2
	s_waitcnt lgkmcnt(0)
	s_add_u32 s28, s6, 0xfffc0080
	s_addc_u32 s29, s7, -1
	s_add_i32 s57, 0, 0x10000
	s_cmp_eq_u32 s56, 12
	s_cselect_b32 s31, s5, s29
	s_cselect_b32 s30, s23, s28
	v_add_u32_e32 v146, s57, v148
	s_cselect_b32 s29, s15, s55
	s_cselect_b32 s28, s47, s54
	s_add_i32 s60, 0, 0x14000
	ds_read_b128 v[142:145], v146
	ds_read_b128 v[152:155], v146 offset:1024
	ds_read_b128 v[156:159], v146 offset:2048
	ds_read_b128 v[160:163], v146 offset:3072
	v_add_u32_e32 v146, s60, v148
	ds_read_b128 v[164:167], v146
	ds_read_b128 v[168:171], v146 offset:1024
	ds_read_b128 v[172:175], v146 offset:2048
	ds_read_b128 v[176:179], v146 offset:3072
	v_lshl_add_u64 v[188:189], s[6:7], 0, v[140:141]
	s_add_i32 m0, s21, 0xc000
	ds_read_b128 v[180:183], v151
	ds_read_b128 v[184:187], v151 offset:1024
	ds_read_b128 v[208:211], v151 offset:2048
	ds_read_b128 v[230:233], v151 offset:3072
	ds_read_b128 v[234:237], v151 offset:4096
	ds_read_b128 v[238:241], v151 offset:5120
	ds_read_b128 v[242:245], v151 offset:6144
	ds_read_b128 v[246:249], v151 offset:7168
	global_load_lds_dwordx4 v[188:189], off
	v_lshl_add_u64 v[188:189], s[6:7], 0, v[138:139]
	s_add_i32 m0, s21, 0xe000
	s_nop 0
	global_load_lds_dwordx4 v[188:189], off
	s_waitcnt vmcnt(8)
	s_waitcnt lgkmcnt(0)
	s_barrier
	s_setprio 1
	s_waitcnt lgkmcnt(0)
	v_mfma_f32_16x16x32_bf16 v[126:129], v[142:145], v[180:183], 0
	v_mfma_f32_16x16x32_bf16 v[122:125], v[156:159], v[180:183], 0
	v_mfma_f32_16x16x32_bf16 v[108:111], v[142:145], v[208:211], 0
	v_mfma_f32_16x16x32_bf16 v[104:107], v[156:159], v[208:211], 0
	v_mfma_f32_16x16x32_bf16 v[92:95], v[142:145], v[234:237], 0
	v_mfma_f32_16x16x32_bf16 v[88:91], v[156:159], v[234:237], 0
	v_mfma_f32_16x16x32_bf16 v[76:79], v[142:145], v[242:245], 0
	v_mfma_f32_16x16x32_bf16 v[72:75], v[156:159], v[242:245], 0
	v_mfma_f32_16x16x32_bf16 v[126:129], v[152:155], v[184:187], v[126:129]
	v_mfma_f32_16x16x32_bf16 v[122:125], v[160:163], v[184:187], v[122:125]
	v_mfma_f32_16x16x32_bf16 v[108:111], v[152:155], v[230:233], v[108:111]
	v_mfma_f32_16x16x32_bf16 v[104:107], v[160:163], v[230:233], v[104:107]
	v_mfma_f32_16x16x32_bf16 v[92:95], v[152:155], v[238:241], v[92:95]
	v_mfma_f32_16x16x32_bf16 v[88:91], v[160:163], v[238:241], v[88:91]
	v_mfma_f32_16x16x32_bf16 v[76:79], v[152:155], v[246:249], v[76:79]
	v_mfma_f32_16x16x32_bf16 v[72:75], v[160:163], v[246:249], v[72:75]
	s_setprio 0
	s_setprio 1
	v_mfma_f32_16x16x32_bf16 v[118:121], v[164:167], v[180:183], 0
	v_mfma_f32_16x16x32_bf16 v[114:117], v[172:175], v[180:183], 0
	v_mfma_f32_16x16x32_bf16 v[100:103], v[164:167], v[208:211], 0
	v_mfma_f32_16x16x32_bf16 v[96:99], v[172:175], v[208:211], 0
	v_mfma_f32_16x16x32_bf16 v[84:87], v[164:167], v[234:237], 0
	v_mfma_f32_16x16x32_bf16 v[80:83], v[172:175], v[234:237], 0
	v_mfma_f32_16x16x32_bf16 v[68:71], v[164:167], v[242:245], 0
	v_mfma_f32_16x16x32_bf16 v[64:67], v[172:175], v[242:245], 0
	v_mfma_f32_16x16x32_bf16 v[118:121], v[168:171], v[184:187], v[118:121]
	v_mfma_f32_16x16x32_bf16 v[114:117], v[176:179], v[184:187], v[114:117]
	v_mfma_f32_16x16x32_bf16 v[100:103], v[168:171], v[230:233], v[100:103]
	v_mfma_f32_16x16x32_bf16 v[96:99], v[176:179], v[230:233], v[96:99]
	v_mfma_f32_16x16x32_bf16 v[84:87], v[168:171], v[238:241], v[84:87]
	v_mfma_f32_16x16x32_bf16 v[80:83], v[176:179], v[238:241], v[80:83]
	v_mfma_f32_16x16x32_bf16 v[68:71], v[168:171], v[246:249], v[68:71]
	v_mfma_f32_16x16x32_bf16 v[64:67], v[176:179], v[246:249], v[64:67]
	s_setprio 0
	s_barrier
	s_add_i32 s57, s57, s39
	v_lshl_add_u64 v[188:189], s[28:29], 0, v[112:113]
	s_mov_b32 m0, s57
	ds_read_b128 v[180:183], v151 offset:16384
	ds_read_b128 v[184:187], v151 offset:17408
	ds_read_b128 v[208:211], v151 offset:18432
	ds_read_b128 v[230:233], v151 offset:19456
	ds_read_b128 v[234:237], v151 offset:20480
	ds_read_b128 v[238:241], v151 offset:21504
	ds_read_b128 v[242:245], v151 offset:22528
	ds_read_b128 v[246:249], v151 offset:23552
	global_load_lds_dwordx4 v[188:189], off
	s_add_i32 m0, s57, 0x2000
	s_add_u32 s58, s28, 0x40000
	v_lshl_add_u64 v[212:213], s[28:29], 0, v[134:135]
	s_addc_u32 s59, s29, 0
	s_add_i32 s57, s60, s39
	global_load_lds_dwordx4 v[212:213], off
	v_lshl_add_u64 v[250:251], s[58:59], 0, v[112:113]
	s_mov_b32 m0, s57
	v_lshl_add_u64 v[252:253], s[30:31], 0, v[132:133]
	global_load_lds_dwordx4 v[250:251], off
	v_lshl_add_u64 v[250:251], s[58:59], 0, v[134:135]
	s_add_i32 m0, s57, 0x2000
	s_nop 0
	global_load_lds_dwordx4 v[250:251], off
	v_lshl_add_u64 v[250:251], s[30:31], 0, v[130:131]
	s_mov_b32 m0, s21
	s_nop 0
	global_load_lds_dwordx4 v[250:251], off
	s_mov_b32 m0, s40
	s_nop 0
	global_load_lds_dwordx4 v[252:253], off
	s_waitcnt vmcnt(8)
	s_waitcnt lgkmcnt(0)
	s_barrier
	s_setprio 1
	s_waitcnt lgkmcnt(0)
	v_mfma_f32_16x16x32_bf16 v[60:63], v[142:145], v[180:183], 0
	v_mfma_f32_16x16x32_bf16 v[56:59], v[156:159], v[180:183], 0
	v_mfma_f32_16x16x32_bf16 v[44:47], v[142:145], v[208:211], 0
	v_mfma_f32_16x16x32_bf16 v[40:43], v[156:159], v[208:211], 0
	v_mfma_f32_16x16x32_bf16 v[28:31], v[142:145], v[234:237], 0
	v_mfma_f32_16x16x32_bf16 v[24:27], v[156:159], v[234:237], 0
	v_mfma_f32_16x16x32_bf16 v[12:15], v[142:145], v[242:245], 0
	v_mfma_f32_16x16x32_bf16 v[8:11], v[156:159], v[242:245], 0
	v_mfma_f32_16x16x32_bf16 v[60:63], v[152:155], v[184:187], v[60:63]
	v_mfma_f32_16x16x32_bf16 v[56:59], v[160:163], v[184:187], v[56:59]
	v_mfma_f32_16x16x32_bf16 v[44:47], v[152:155], v[230:233], v[44:47]
	v_mfma_f32_16x16x32_bf16 v[40:43], v[160:163], v[230:233], v[40:43]
	v_mfma_f32_16x16x32_bf16 v[28:31], v[152:155], v[238:241], v[28:31]
	v_mfma_f32_16x16x32_bf16 v[24:27], v[160:163], v[238:241], v[24:27]
	v_mfma_f32_16x16x32_bf16 v[12:15], v[152:155], v[246:249], v[12:15]
	v_mfma_f32_16x16x32_bf16 v[8:11], v[160:163], v[246:249], v[8:11]
	s_setprio 0
	s_setprio 1
	v_mfma_f32_16x16x32_bf16 v[52:55], v[164:167], v[180:183], 0
	v_mfma_f32_16x16x32_bf16 v[48:51], v[172:175], v[180:183], 0
	v_mfma_f32_16x16x32_bf16 v[36:39], v[164:167], v[208:211], 0
	v_mfma_f32_16x16x32_bf16 v[32:35], v[172:175], v[208:211], 0
	v_mfma_f32_16x16x32_bf16 v[20:23], v[164:167], v[234:237], 0
	v_mfma_f32_16x16x32_bf16 v[16:19], v[172:175], v[234:237], 0
	v_mfma_f32_16x16x32_bf16 v[4:7], v[164:167], v[242:245], 0
	v_mfma_f32_16x16x32_bf16 v[0:3], v[172:175], v[242:245], 0
	v_mfma_f32_16x16x32_bf16 v[52:55], v[168:171], v[184:187], v[52:55]
	v_mfma_f32_16x16x32_bf16 v[48:51], v[176:179], v[184:187], v[48:51]
	v_mfma_f32_16x16x32_bf16 v[36:39], v[168:171], v[230:233], v[36:39]
	v_mfma_f32_16x16x32_bf16 v[32:35], v[176:179], v[230:233], v[32:35]
	v_mfma_f32_16x16x32_bf16 v[20:23], v[168:171], v[238:241], v[20:23]
	v_mfma_f32_16x16x32_bf16 v[16:19], v[176:179], v[238:241], v[16:19]
	v_mfma_f32_16x16x32_bf16 v[4:7], v[168:171], v[246:249], v[4:7]
	v_mfma_f32_16x16x32_bf16 v[0:3], v[176:179], v[246:249], v[0:3]
	s_setprio 0
	s_barrier
	s_add_i32 s57, 0, 0x18000
	v_add_u32_e32 v146, s57, v148
	s_add_i32 s58, 0, 0x1c000
	ds_read_b128 v[142:145], v146
	ds_read_b128 v[152:155], v146 offset:1024
	ds_read_b128 v[156:159], v146 offset:2048
	ds_read_b128 v[160:163], v146 offset:3072
	v_add_u32_e32 v146, s58, v148
	ds_read_b128 v[164:167], v146
	ds_read_b128 v[168:171], v146 offset:1024
	ds_read_b128 v[172:175], v146 offset:2048
	ds_read_b128 v[176:179], v146 offset:3072
	s_add_u32 s30, s30, 0x40000
	s_addc_u32 s31, s31, 0
	s_mov_b32 m0, s41
	v_lshl_add_u64 v[228:229], s[30:31], 0, v[130:131]
	ds_read_b128 v[180:183], v151 offset:32768
	ds_read_b128 v[184:187], v151 offset:33792
	ds_read_b128 v[208:211], v151 offset:34816
	ds_read_b128 v[230:233], v151 offset:35840
	ds_read_b128 v[234:237], v151 offset:36864
	ds_read_b128 v[238:241], v151 offset:37888
	ds_read_b128 v[242:245], v151 offset:38912
	ds_read_b128 v[246:249], v151 offset:39936
	global_load_lds_dwordx4 v[228:229], off
	v_lshl_add_u64 v[228:229], s[30:31], 0, v[132:133]
	s_mov_b32 m0, s42
	s_nop 0
	global_load_lds_dwordx4 v[228:229], off
	s_waitcnt vmcnt(8)
	s_waitcnt lgkmcnt(0)
	s_barrier
	s_setprio 1
	s_waitcnt lgkmcnt(0)
	v_mfma_f32_16x16x32_bf16 v[126:129], v[142:145], v[180:183], v[126:129]
	v_mfma_f32_16x16x32_bf16 v[122:125], v[156:159], v[180:183], v[122:125]
	v_mfma_f32_16x16x32_bf16 v[108:111], v[142:145], v[208:211], v[108:111]
	v_mfma_f32_16x16x32_bf16 v[104:107], v[156:159], v[208:211], v[104:107]
	v_mfma_f32_16x16x32_bf16 v[92:95], v[142:145], v[234:237], v[92:95]
	v_mfma_f32_16x16x32_bf16 v[88:91], v[156:159], v[234:237], v[88:91]
	v_mfma_f32_16x16x32_bf16 v[76:79], v[142:145], v[242:245], v[76:79]
	v_mfma_f32_16x16x32_bf16 v[72:75], v[156:159], v[242:245], v[72:75]
	v_mfma_f32_16x16x32_bf16 v[126:129], v[152:155], v[184:187], v[126:129]
	v_mfma_f32_16x16x32_bf16 v[122:125], v[160:163], v[184:187], v[122:125]
	v_mfma_f32_16x16x32_bf16 v[108:111], v[152:155], v[230:233], v[108:111]
	v_mfma_f32_16x16x32_bf16 v[104:107], v[160:163], v[230:233], v[104:107]
	v_mfma_f32_16x16x32_bf16 v[92:95], v[152:155], v[238:241], v[92:95]
	v_mfma_f32_16x16x32_bf16 v[88:91], v[160:163], v[238:241], v[88:91]
	v_mfma_f32_16x16x32_bf16 v[76:79], v[152:155], v[246:249], v[76:79]
	v_mfma_f32_16x16x32_bf16 v[72:75], v[160:163], v[246:249], v[72:75]
	s_setprio 0
	s_setprio 1
	v_mfma_f32_16x16x32_bf16 v[118:121], v[164:167], v[180:183], v[118:121]
	v_mfma_f32_16x16x32_bf16 v[114:117], v[172:175], v[180:183], v[114:117]
	v_mfma_f32_16x16x32_bf16 v[100:103], v[164:167], v[208:211], v[100:103]
	v_mfma_f32_16x16x32_bf16 v[96:99], v[172:175], v[208:211], v[96:99]
	v_mfma_f32_16x16x32_bf16 v[84:87], v[164:167], v[234:237], v[84:87]
	v_mfma_f32_16x16x32_bf16 v[80:83], v[172:175], v[234:237], v[80:83]
	v_mfma_f32_16x16x32_bf16 v[68:71], v[164:167], v[242:245], v[68:71]
	v_mfma_f32_16x16x32_bf16 v[64:67], v[172:175], v[242:245], v[64:67]
	v_mfma_f32_16x16x32_bf16 v[118:121], v[168:171], v[184:187], v[118:121]
	v_mfma_f32_16x16x32_bf16 v[114:117], v[176:179], v[184:187], v[114:117]
	v_mfma_f32_16x16x32_bf16 v[100:103], v[168:171], v[230:233], v[100:103]
	v_mfma_f32_16x16x32_bf16 v[96:99], v[176:179], v[230:233], v[96:99]
	v_mfma_f32_16x16x32_bf16 v[84:87], v[168:171], v[238:241], v[84:87]
	v_mfma_f32_16x16x32_bf16 v[80:83], v[176:179], v[238:241], v[80:83]
	v_mfma_f32_16x16x32_bf16 v[68:71], v[168:171], v[246:249], v[68:71]
	v_mfma_f32_16x16x32_bf16 v[64:67], v[176:179], v[246:249], v[64:67]
	s_setprio 0
	s_barrier
	s_add_i32 s30, s57, s39
	v_lshl_add_u64 v[188:189], v[188:189], 0, s[96:97]
	s_mov_b32 m0, s30
	ds_read_b128 v[180:183], v151 offset:49152
	ds_read_b128 v[184:187], v151 offset:50176
	ds_read_b128 v[208:211], v151 offset:51200
	ds_read_b128 v[230:233], v151 offset:52224
	ds_read_b128 v[234:237], v151 offset:53248
	ds_read_b128 v[238:241], v151 offset:54272
	ds_read_b128 v[242:245], v151 offset:55296
	ds_read_b128 v[246:249], v151 offset:56320
	global_load_lds_dwordx4 v[188:189], off
	s_add_i32 m0, s30, 0x2000
	s_add_u32 s28, s28, 0x40080
	v_lshl_add_u64 v[188:189], v[212:213], 0, s[96:97]
	s_addc_u32 s29, s29, 0
	s_add_i32 s30, s58, s39
	global_load_lds_dwordx4 v[188:189], off
	v_lshl_add_u64 v[188:189], s[28:29], 0, v[112:113]
	s_mov_b32 m0, s30
	s_nop 0
	global_load_lds_dwordx4 v[188:189], off
	v_lshl_add_u64 v[188:189], s[28:29], 0, v[134:135]
	s_add_i32 m0, s30, 0x2000
	s_nop 0
	global_load_lds_dwordx4 v[188:189], off
	v_lshl_add_u64 v[188:189], v[250:251], 0, s[96:97]
	s_mov_b32 m0, s43
	s_nop 0
	global_load_lds_dwordx4 v[188:189], off
	v_lshl_add_u64 v[188:189], v[252:253], 0, s[96:97]
	s_mov_b32 m0, s44
	s_nop 0
	global_load_lds_dwordx4 v[188:189], off
	s_waitcnt vmcnt(8)
	s_waitcnt lgkmcnt(0)
	s_barrier
	s_setprio 1
	s_waitcnt lgkmcnt(0)
	v_mfma_f32_16x16x32_bf16 v[60:63], v[142:145], v[180:183], v[60:63]
	v_mfma_f32_16x16x32_bf16 v[56:59], v[156:159], v[180:183], v[56:59]
	v_mfma_f32_16x16x32_bf16 v[44:47], v[142:145], v[208:211], v[44:47]
	v_mfma_f32_16x16x32_bf16 v[40:43], v[156:159], v[208:211], v[40:43]
	v_mfma_f32_16x16x32_bf16 v[28:31], v[142:145], v[234:237], v[28:31]
	v_mfma_f32_16x16x32_bf16 v[24:27], v[156:159], v[234:237], v[24:27]
	v_mfma_f32_16x16x32_bf16 v[12:15], v[142:145], v[242:245], v[12:15]
	v_mfma_f32_16x16x32_bf16 v[8:11], v[156:159], v[242:245], v[8:11]
	v_mfma_f32_16x16x32_bf16 v[60:63], v[152:155], v[184:187], v[60:63]
	v_mfma_f32_16x16x32_bf16 v[56:59], v[160:163], v[184:187], v[56:59]
	v_mfma_f32_16x16x32_bf16 v[44:47], v[152:155], v[230:233], v[44:47]
	v_mfma_f32_16x16x32_bf16 v[40:43], v[160:163], v[230:233], v[40:43]
	v_mfma_f32_16x16x32_bf16 v[28:31], v[152:155], v[238:241], v[28:31]
	v_mfma_f32_16x16x32_bf16 v[24:27], v[160:163], v[238:241], v[24:27]
	v_mfma_f32_16x16x32_bf16 v[12:15], v[152:155], v[246:249], v[12:15]
	v_mfma_f32_16x16x32_bf16 v[8:11], v[160:163], v[246:249], v[8:11]
	s_setprio 0
	s_setprio 1
	v_mfma_f32_16x16x32_bf16 v[52:55], v[164:167], v[180:183], v[52:55]
	v_mfma_f32_16x16x32_bf16 v[48:51], v[172:175], v[180:183], v[48:51]
	v_mfma_f32_16x16x32_bf16 v[36:39], v[164:167], v[208:211], v[36:39]
	v_mfma_f32_16x16x32_bf16 v[32:35], v[172:175], v[208:211], v[32:35]
	v_mfma_f32_16x16x32_bf16 v[20:23], v[164:167], v[234:237], v[20:23]
	v_mfma_f32_16x16x32_bf16 v[16:19], v[172:175], v[234:237], v[16:19]
	v_mfma_f32_16x16x32_bf16 v[4:7], v[164:167], v[242:245], v[4:7]
	v_mfma_f32_16x16x32_bf16 v[0:3], v[172:175], v[242:245], v[0:3]
	v_mfma_f32_16x16x32_bf16 v[52:55], v[168:171], v[184:187], v[52:55]
	v_mfma_f32_16x16x32_bf16 v[48:51], v[176:179], v[184:187], v[48:51]
	v_mfma_f32_16x16x32_bf16 v[36:39], v[168:171], v[230:233], v[36:39]
	v_mfma_f32_16x16x32_bf16 v[32:35], v[176:179], v[230:233], v[32:35]
	v_mfma_f32_16x16x32_bf16 v[20:23], v[168:171], v[238:241], v[20:23]
	v_mfma_f32_16x16x32_bf16 v[16:19], v[176:179], v[238:241], v[16:19]
	v_mfma_f32_16x16x32_bf16 v[4:7], v[168:171], v[246:249], v[4:7]
	v_mfma_f32_16x16x32_bf16 v[0:3], v[176:179], v[246:249], v[0:3]
	s_setprio 0
	s_barrier
	s_add_i32 s56, s56, 2
	s_add_u32 s54, s54, 0x100
	s_addc_u32 s55, s55, 0
	s_add_u32 s6, s6, 0x100
	s_addc_u32 s7, s7, 0
	s_cmp_gt_u32 s56, 13
	s_cbranch_scc0 .LBB0_2369
	s_branch .Lpeel_exit_2369

.Lpeel_exit_2369:
	s_and_b64 vcc, exec, s[16:17]
	s_cbranch_vccz .LBB0_2372
	s_barrier
